# phase E: a quarter of each gate tile stays in the 32 KB of LDS the GEMM leaves free (less scratch traffic); branch epilogue hand-written with wide loads and stores
# speedup vs baseline: 1.0611x; 1.0150x over previous
; __device__ __forceinline__ float bflo(unsigned u) { return __uint_as_float(u << 16); }
; __device__ __forceinline__ float bfhi(unsigned u) { return __uint_as_float(u & 0xFFFF0000u); }
; __device__ __forceinline__ void phaseE(const Params& p, int layer) {
;     ...
;               uint4 g4[2]; uint2 old[2][2];
; #pragma unroll
;               for (int mm = 0; mm < 2; mm++) {
;                 const int m = mh * 2 + mm;
;                 g4[mm] = *(const uint4*)(gsb + ((ai * 2 + bj) * 4 + m) * 8192 + gs_lane);
;                 if (br) {
; #pragma unroll
;                   for (int n = 0; n < 2; n++)
;                     old[mm][n] = *(const uint2*)(mb + ((size_t)(ai * 128 + m * 16) * 2048 + bj * 128 + n * 16) * 2 + lane_m);
;                 }
;               }
; #pragma unroll
;               for (int mm = 0; mm < 2; mm++) {
;                 const int m = mh * 2 + mm;
;                 const unsigned gq[4] = {g4[mm].x, g4[mm].y, g4[mm].z, g4[mm].w};
; #pragma unroll
;                 for (int n = 0; n < 2; n++) {
;                   f32x4 v = acc[ai][bj][m][n];
;                   float o0 = bflo(gq[2 * n]) * v[0], o1 = bfhi(gq[2 * n]) * v[1], o2 = bflo(gq[2 * n + 1]) * v[2], o3 = bfhi(gq[2 * n + 1]) * v[3];
;                   char* mp = mb + ((size_t)(ai * 128 + m * 16) * 2048 + bj * 128 + n * 16) * 2 + lane_m;
;                   if (br) { o0 += bflo(old[mm][n].x); o1 += bfhi(old[mm][n].x); o2 += bflo(old[mm][n].y); o3 += bfhi(old[mm][n].y); }
;                   *(uint2*)mp = make_uint2(pk2(o0, o1), pk2(o2, o3));
;                 }
;               }
.LBB0_2323:
	v_readlane_b32 s0, v253, 51
	v_readlane_b32 s1, v253, 52
	v_add_u32_e32 v165, 0x20000, v160
	v_and_b32_e32 v163, 63, v162
	v_add_u32_e32 v163, v163, v162
	s_cmp_lg_u64 s[12:13], 0
	s_nop 3
	s_cbranch_scc0 .Lbrepi_first
	ds_read_b128 v[128:131], v165
	global_load_dwordx4 v[132:135], v163, s[6:7]
	ds_read_b128 v[136:139], v165 offset:8192
	v_add_u32_e32 v210, 0x10000, v163
	global_load_dwordx4 v[140:143], v210, s[6:7]
	ds_read_b128 v[148:151], v165 offset:16384
	v_add_u32_e32 v211, 0x20000, v163
	global_load_dwordx4 v[152:155], v211, s[6:7]
	ds_read_b128 v[164:167], v165 offset:24576
	v_add_u32_e32 v210, 0x30000, v163
	global_load_dwordx4 v[168:171], v210, s[6:7]
	v_add_u32_e32 v146, 0x8000, v160
	global_load_dwordx4 v[172:175], v146, s[0:1]
	global_load_dwordx4 v[176:179], v163, s[6:7] offset:256
	v_add_u32_e32 v147, 0xa000, v160
	global_load_dwordx4 v[180:183], v147, s[0:1]
	v_add_u32_e32 v211, 0x10000, v163
	global_load_dwordx4 v[184:187], v211, s[6:7] offset:256
	v_add_u32_e32 v146, 0xc000, v160
	global_load_dwordx4 v[188:191], v146, s[0:1]
	v_add_u32_e32 v210, 0x20000, v163
	global_load_dwordx4 v[192:195], v210, s[6:7] offset:256
	v_add_u32_e32 v147, 0xe000, v160
	global_load_dwordx4 v[212:215], v147, s[0:1]
	v_add_u32_e32 v211, 0x30000, v163
	global_load_dwordx4 v[216:219], v211, s[6:7] offset:256
	v_add_u32_e32 v146, 0x10000, v160
	global_load_dwordx4 v[220:223], v146, s[0:1]
	v_add_u32_e32 v210, 0x80000, v163
	global_load_dwordx4 v[224:227], v210, s[6:7]
	v_add_u32_e32 v147, 0x12000, v160
	global_load_dwordx4 v[228:231], v147, s[0:1]
	v_add_u32_e32 v211, 0x90000, v163
	global_load_dwordx4 v[232:235], v211, s[6:7]
	v_add_u32_e32 v146, 0x14000, v160
	global_load_dwordx4 v[236:239], v146, s[0:1]
	v_add_u32_e32 v210, 0xa0000, v163
	global_load_dwordx4 v[240:243], v210, s[6:7]
	s_waitcnt vmcnt(17) lgkmcnt(0)
	v_permlane16_swap_b32_e32 v132, v134
	v_permlane16_swap_b32_e32 v133, v135
	v_lshlrev_b32_e32 v156, 16, v128
	v_and_b32_e32 v157, 0xffff0000, v128
	v_lshlrev_b32_e32 v158, 16, v129
	v_and_b32_e32 v159, 0xffff0000, v129
	v_pk_mul_f32 v[156:157], v[124:125], v[156:157]
	v_pk_mul_f32 v[158:159], v[126:127], v[158:159]
	v_permlane32_swap_b32_e32 v132, v134
	v_permlane32_swap_b32_e32 v133, v135
	v_lshlrev_b32_e32 v244, 16, v130
	v_and_b32_e32 v245, 0xffff0000, v130
	v_lshlrev_b32_e32 v246, 16, v131
	v_and_b32_e32 v247, 0xffff0000, v131
	v_pk_mul_f32 v[244:245], v[120:121], v[244:245]
	v_pk_mul_f32 v[246:247], v[122:123], v[246:247]
	v_lshlrev_b32_e32 v196, 16, v132
	v_and_b32_e32 v197, 0xffff0000, v132
	v_lshlrev_b32_e32 v198, 16, v133
	v_and_b32_e32 v199, 0xffff0000, v133
	v_pk_add_f32 v[156:157], v[156:157], v[196:197]
	v_pk_add_f32 v[158:159], v[158:159], v[198:199]
	v_lshlrev_b32_e32 v200, 16, v134
	v_and_b32_e32 v201, 0xffff0000, v134
	v_lshlrev_b32_e32 v204, 16, v135
	v_and_b32_e32 v205, 0xffff0000, v135
	v_pk_add_f32 v[244:245], v[244:245], v[200:201]
	v_pk_add_f32 v[246:247], v[246:247], v[204:205]
	v_cvt_pk_bf16_f32 v156, v156, v157
	v_cvt_pk_bf16_f32 v157, v158, v159
	v_cvt_pk_bf16_f32 v158, v244, v245
	v_cvt_pk_bf16_f32 v159, v246, v247
	s_nop 1
	v_permlane32_swap_b32_e32 v156, v158
	v_permlane32_swap_b32_e32 v157, v159
	s_nop 0
	v_permlane16_swap_b32_e32 v156, v158
	v_permlane16_swap_b32_e32 v157, v159
	global_store_dwordx4 v163, v[156:159], s[6:7]
	v_add_u32_e32 v147, 0x16000, v160
	global_load_dwordx4 v[128:131], v147, s[0:1]
	v_add_u32_e32 v211, 0xb0000, v163
	global_load_dwordx4 v[132:135], v211, s[6:7]
	s_waitcnt vmcnt(19) lgkmcnt(0)
	v_permlane16_swap_b32_e32 v140, v142
	v_permlane16_swap_b32_e32 v141, v143
	v_lshlrev_b32_e32 v156, 16, v136
	v_and_b32_e32 v157, 0xffff0000, v136
	v_lshlrev_b32_e32 v158, 16, v137
	v_and_b32_e32 v159, 0xffff0000, v137
	v_pk_mul_f32 v[156:157], v[116:117], v[156:157]
	v_pk_mul_f32 v[158:159], v[118:119], v[158:159]
	v_permlane32_swap_b32_e32 v140, v142
	v_permlane32_swap_b32_e32 v141, v143
	v_lshlrev_b32_e32 v244, 16, v138
	v_and_b32_e32 v245, 0xffff0000, v138
	v_lshlrev_b32_e32 v246, 16, v139
	v_and_b32_e32 v247, 0xffff0000, v139
	v_pk_mul_f32 v[244:245], v[112:113], v[244:245]
	v_pk_mul_f32 v[246:247], v[114:115], v[246:247]
	v_lshlrev_b32_e32 v196, 16, v140
	v_and_b32_e32 v197, 0xffff0000, v140
	v_lshlrev_b32_e32 v198, 16, v141
	v_and_b32_e32 v199, 0xffff0000, v141
	v_pk_add_f32 v[156:157], v[156:157], v[196:197]
	v_pk_add_f32 v[158:159], v[158:159], v[198:199]
	v_lshlrev_b32_e32 v200, 16, v142
	v_and_b32_e32 v201, 0xffff0000, v142
	v_lshlrev_b32_e32 v204, 16, v143
	v_and_b32_e32 v205, 0xffff0000, v143
	v_pk_add_f32 v[244:245], v[244:245], v[200:201]
	v_pk_add_f32 v[246:247], v[246:247], v[204:205]
	v_cvt_pk_bf16_f32 v156, v156, v157
	v_cvt_pk_bf16_f32 v157, v158, v159
	v_cvt_pk_bf16_f32 v158, v244, v245
	v_cvt_pk_bf16_f32 v159, v246, v247
	v_add_u32_e32 v210, 0x10000, v163
	s_nop 1
	v_permlane32_swap_b32_e32 v156, v158
	v_permlane32_swap_b32_e32 v157, v159
	s_nop 0
	v_permlane16_swap_b32_e32 v156, v158
	v_permlane16_swap_b32_e32 v157, v159
	global_store_dwordx4 v210, v[156:159], s[6:7]
	v_add_u32_e32 v146, 0x18000, v160
	global_load_dwordx4 v[136:139], v146, s[0:1]
	v_add_u32_e32 v211, 0x80000, v163
	global_load_dwordx4 v[140:143], v211, s[6:7] offset:256
	s_waitcnt vmcnt(21) lgkmcnt(0)
; __device__ __forceinline__ float bflo(unsigned u) { return __uint_as_float(u << 16); }
; __device__ __forceinline__ float bfhi(unsigned u) { return __uint_as_float(u & 0xFFFF0000u); }
; __device__ __forceinline__ void phaseE(const Params& p, int layer) {
;     ...
;               uint4 g4[2]; uint2 old[2][2];
; #pragma unroll
;               for (int mm = 0; mm < 2; mm++) {
;                 const int m = mh * 2 + mm;
;                 g4[mm] = *(const uint4*)(gsb + ((ai * 2 + bj) * 4 + m) * 8192 + gs_lane);
;                 if (br) {
; #pragma unroll
;                   for (int n = 0; n < 2; n++)
;                     old[mm][n] = *(const uint2*)(mb + ((size_t)(ai * 128 + m * 16) * 2048 + bj * 128 + n * 16) * 2 + lane_m);
;                 }
;               }
; #pragma unroll
;               for (int mm = 0; mm < 2; mm++) {
;                 const int m = mh * 2 + mm;
;                 const unsigned gq[4] = {g4[mm].x, g4[mm].y, g4[mm].z, g4[mm].w};
; #pragma unroll
;                 for (int n = 0; n < 2; n++) {
;                   f32x4 v = acc[ai][bj][m][n];
;                   float o0 = bflo(gq[2 * n]) * v[0], o1 = bfhi(gq[2 * n]) * v[1], o2 = bflo(gq[2 * n + 1]) * v[2], o3 = bfhi(gq[2 * n + 1]) * v[3];
;                   char* mp = mb + ((size_t)(ai * 128 + m * 16) * 2048 + bj * 128 + n * 16) * 2 + lane_m;
;                   if (br) { o0 += bflo(old[mm][n].x); o1 += bfhi(old[mm][n].x); o2 += bflo(old[mm][n].y); o3 += bfhi(old[mm][n].y); }
;                   *(uint2*)mp = make_uint2(pk2(o0, o1), pk2(o2, o3));
;                 }
;               }
	v_permlane16_swap_b32_e32 v152, v154
	v_permlane16_swap_b32_e32 v153, v155
	v_lshlrev_b32_e32 v156, 16, v148
	v_and_b32_e32 v157, 0xffff0000, v148
	v_lshlrev_b32_e32 v158, 16, v149
	v_and_b32_e32 v159, 0xffff0000, v149
	v_pk_mul_f32 v[156:157], v[108:109], v[156:157]
	v_pk_mul_f32 v[158:159], v[110:111], v[158:159]
	v_permlane32_swap_b32_e32 v152, v154
	v_permlane32_swap_b32_e32 v153, v155
	v_lshlrev_b32_e32 v244, 16, v150
	v_and_b32_e32 v245, 0xffff0000, v150
	v_lshlrev_b32_e32 v246, 16, v151
	v_and_b32_e32 v247, 0xffff0000, v151
	v_pk_mul_f32 v[244:245], v[104:105], v[244:245]
	v_pk_mul_f32 v[246:247], v[106:107], v[246:247]
	v_lshlrev_b32_e32 v196, 16, v152
	v_and_b32_e32 v197, 0xffff0000, v152
	v_lshlrev_b32_e32 v198, 16, v153
	v_and_b32_e32 v199, 0xffff0000, v153
	v_pk_add_f32 v[156:157], v[156:157], v[196:197]
	v_pk_add_f32 v[158:159], v[158:159], v[198:199]
	v_lshlrev_b32_e32 v200, 16, v154
	v_and_b32_e32 v201, 0xffff0000, v154
	v_lshlrev_b32_e32 v204, 16, v155
	v_and_b32_e32 v205, 0xffff0000, v155
	v_pk_add_f32 v[244:245], v[244:245], v[200:201]
	v_pk_add_f32 v[246:247], v[246:247], v[204:205]
	v_cvt_pk_bf16_f32 v156, v156, v157
	v_cvt_pk_bf16_f32 v157, v158, v159
	v_cvt_pk_bf16_f32 v158, v244, v245
	v_cvt_pk_bf16_f32 v159, v246, v247
	v_add_u32_e32 v210, 0x20000, v163
	s_nop 1
	v_permlane32_swap_b32_e32 v156, v158
	v_permlane32_swap_b32_e32 v157, v159
	s_nop 0
	v_permlane16_swap_b32_e32 v156, v158
	v_permlane16_swap_b32_e32 v157, v159
	global_store_dwordx4 v210, v[156:159], s[6:7]
	v_add_u32_e32 v147, 0x1a000, v160
	global_load_dwordx4 v[148:151], v147, s[0:1]
	v_add_u32_e32 v211, 0x90000, v163
	global_load_dwordx4 v[152:155], v211, s[6:7] offset:256
	s_waitcnt vmcnt(23) lgkmcnt(0)
	v_permlane16_swap_b32_e32 v168, v170
	v_permlane16_swap_b32_e32 v169, v171
	v_lshlrev_b32_e32 v156, 16, v164
	v_and_b32_e32 v157, 0xffff0000, v164
	v_lshlrev_b32_e32 v158, 16, v165
	v_and_b32_e32 v159, 0xffff0000, v165
	v_pk_mul_f32 v[156:157], v[100:101], v[156:157]
	v_pk_mul_f32 v[158:159], v[102:103], v[158:159]
	v_permlane32_swap_b32_e32 v168, v170
	v_permlane32_swap_b32_e32 v169, v171
	v_lshlrev_b32_e32 v244, 16, v166
	v_and_b32_e32 v245, 0xffff0000, v166
	v_lshlrev_b32_e32 v246, 16, v167
	v_and_b32_e32 v247, 0xffff0000, v167
	v_pk_mul_f32 v[244:245], v[96:97], v[244:245]
	v_pk_mul_f32 v[246:247], v[98:99], v[246:247]
	v_lshlrev_b32_e32 v196, 16, v168
	v_and_b32_e32 v197, 0xffff0000, v168
	v_lshlrev_b32_e32 v198, 16, v169
	v_and_b32_e32 v199, 0xffff0000, v169
	v_pk_add_f32 v[156:157], v[156:157], v[196:197]
	v_pk_add_f32 v[158:159], v[158:159], v[198:199]
	v_lshlrev_b32_e32 v200, 16, v170
	v_and_b32_e32 v201, 0xffff0000, v170
	v_lshlrev_b32_e32 v204, 16, v171
	v_and_b32_e32 v205, 0xffff0000, v171
	v_pk_add_f32 v[244:245], v[244:245], v[200:201]
	v_pk_add_f32 v[246:247], v[246:247], v[204:205]
	v_cvt_pk_bf16_f32 v156, v156, v157
	v_cvt_pk_bf16_f32 v157, v158, v159
	v_cvt_pk_bf16_f32 v158, v244, v245
	v_cvt_pk_bf16_f32 v159, v246, v247
	v_add_u32_e32 v210, 0x30000, v163
	s_nop 1
	v_permlane32_swap_b32_e32 v156, v158
	v_permlane32_swap_b32_e32 v157, v159
	s_nop 0
	v_permlane16_swap_b32_e32 v156, v158
	v_permlane16_swap_b32_e32 v157, v159
	global_store_dwordx4 v210, v[156:159], s[6:7]
	v_add_u32_e32 v146, 0x1c000, v160
	global_load_dwordx4 v[164:167], v146, s[0:1]
	v_add_u32_e32 v211, 0xa0000, v163
	global_load_dwordx4 v[168:171], v211, s[6:7] offset:256
	s_waitcnt vmcnt(24)
	v_permlane16_swap_b32_e32 v176, v178
	v_permlane16_swap_b32_e32 v177, v179
	v_lshlrev_b32_e32 v156, 16, v172
	v_and_b32_e32 v157, 0xffff0000, v172
	v_lshlrev_b32_e32 v158, 16, v173
	v_and_b32_e32 v159, 0xffff0000, v173
	v_pk_mul_f32 v[156:157], v[92:93], v[156:157]
	v_pk_mul_f32 v[158:159], v[94:95], v[158:159]
	v_permlane32_swap_b32_e32 v176, v178
	v_permlane32_swap_b32_e32 v177, v179
	v_lshlrev_b32_e32 v244, 16, v174
	v_and_b32_e32 v245, 0xffff0000, v174
	v_lshlrev_b32_e32 v246, 16, v175
	v_and_b32_e32 v247, 0xffff0000, v175
	v_pk_mul_f32 v[244:245], v[88:89], v[244:245]
	v_pk_mul_f32 v[246:247], v[90:91], v[246:247]
	v_lshlrev_b32_e32 v196, 16, v176
	v_and_b32_e32 v197, 0xffff0000, v176
	v_lshlrev_b32_e32 v198, 16, v177
	v_and_b32_e32 v199, 0xffff0000, v177
	v_pk_add_f32 v[156:157], v[156:157], v[196:197]
	v_pk_add_f32 v[158:159], v[158:159], v[198:199]
	v_lshlrev_b32_e32 v200, 16, v178
	v_and_b32_e32 v201, 0xffff0000, v178
	v_lshlrev_b32_e32 v204, 16, v179
	v_and_b32_e32 v205, 0xffff0000, v179
	v_pk_add_f32 v[244:245], v[244:245], v[200:201]
	v_pk_add_f32 v[246:247], v[246:247], v[204:205]
	v_cvt_pk_bf16_f32 v156, v156, v157
	v_cvt_pk_bf16_f32 v157, v158, v159
	v_cvt_pk_bf16_f32 v158, v244, v245
	v_cvt_pk_bf16_f32 v159, v246, v247
	s_nop 1
	v_permlane32_swap_b32_e32 v156, v158
	v_permlane32_swap_b32_e32 v157, v159
	s_nop 0
	v_permlane16_swap_b32_e32 v156, v158
	v_permlane16_swap_b32_e32 v157, v159
	global_store_dwordx4 v163, v[156:159], s[6:7] offset:256
	v_add_u32_e32 v147, 0x1e000, v160
	global_load_dwordx4 v[172:175], v147, s[0:1]
	v_add_u32_e32 v210, 0xb0000, v163
	global_load_dwordx4 v[176:179], v210, s[6:7] offset:256
	s_waitcnt vmcnt(25)
; __device__ __forceinline__ float bflo(unsigned u) { return __uint_as_float(u << 16); }
; __device__ __forceinline__ float bfhi(unsigned u) { return __uint_as_float(u & 0xFFFF0000u); }
; __device__ __forceinline__ void phaseE(const Params& p, int layer) {
;     ...
;               uint4 g4[2]; uint2 old[2][2];
; #pragma unroll
;               for (int mm = 0; mm < 2; mm++) {
;                 const int m = mh * 2 + mm;
;                 g4[mm] = *(const uint4*)(gsb + ((ai * 2 + bj) * 4 + m) * 8192 + gs_lane);
;                 if (br) {
; #pragma unroll
;                   for (int n = 0; n < 2; n++)
;                     old[mm][n] = *(const uint2*)(mb + ((size_t)(ai * 128 + m * 16) * 2048 + bj * 128 + n * 16) * 2 + lane_m);
;                 }
;               }
; #pragma unroll
;               for (int mm = 0; mm < 2; mm++) {
;                 const int m = mh * 2 + mm;
;                 const unsigned gq[4] = {g4[mm].x, g4[mm].y, g4[mm].z, g4[mm].w};
; #pragma unroll
;                 for (int n = 0; n < 2; n++) {
;                   f32x4 v = acc[ai][bj][m][n];
;                   float o0 = bflo(gq[2 * n]) * v[0], o1 = bfhi(gq[2 * n]) * v[1], o2 = bflo(gq[2 * n + 1]) * v[2], o3 = bfhi(gq[2 * n + 1]) * v[3];
;                   char* mp = mb + ((size_t)(ai * 128 + m * 16) * 2048 + bj * 128 + n * 16) * 2 + lane_m;
;                   if (br) { o0 += bflo(old[mm][n].x); o1 += bfhi(old[mm][n].x); o2 += bflo(old[mm][n].y); o3 += bfhi(old[mm][n].y); }
;                   *(uint2*)mp = make_uint2(pk2(o0, o1), pk2(o2, o3));
;                 }
;               }
	v_permlane16_swap_b32_e32 v184, v186
	v_permlane16_swap_b32_e32 v185, v187
	v_lshlrev_b32_e32 v156, 16, v180
	v_and_b32_e32 v157, 0xffff0000, v180
	v_lshlrev_b32_e32 v158, 16, v181
	v_and_b32_e32 v159, 0xffff0000, v181
	v_pk_mul_f32 v[156:157], v[84:85], v[156:157]
	v_pk_mul_f32 v[158:159], v[86:87], v[158:159]
	v_permlane32_swap_b32_e32 v184, v186
	v_permlane32_swap_b32_e32 v185, v187
	v_lshlrev_b32_e32 v244, 16, v182
	v_and_b32_e32 v245, 0xffff0000, v182
	v_lshlrev_b32_e32 v246, 16, v183
	v_and_b32_e32 v247, 0xffff0000, v183
	v_pk_mul_f32 v[244:245], v[80:81], v[244:245]
	v_pk_mul_f32 v[246:247], v[82:83], v[246:247]
	v_lshlrev_b32_e32 v196, 16, v184
	v_and_b32_e32 v197, 0xffff0000, v184
	v_lshlrev_b32_e32 v198, 16, v185
	v_and_b32_e32 v199, 0xffff0000, v185
	v_pk_add_f32 v[156:157], v[156:157], v[196:197]
	v_pk_add_f32 v[158:159], v[158:159], v[198:199]
	v_lshlrev_b32_e32 v200, 16, v186
	v_and_b32_e32 v201, 0xffff0000, v186
	v_lshlrev_b32_e32 v204, 16, v187
	v_and_b32_e32 v205, 0xffff0000, v187
	v_pk_add_f32 v[244:245], v[244:245], v[200:201]
	v_pk_add_f32 v[246:247], v[246:247], v[204:205]
	v_cvt_pk_bf16_f32 v156, v156, v157
	v_cvt_pk_bf16_f32 v157, v158, v159
	v_cvt_pk_bf16_f32 v158, v244, v245
	v_cvt_pk_bf16_f32 v159, v246, v247
	v_add_u32_e32 v211, 0x10000, v163
	s_nop 1
	v_permlane32_swap_b32_e32 v156, v158
	v_permlane32_swap_b32_e32 v157, v159
	s_nop 0
	v_permlane16_swap_b32_e32 v156, v158
	v_permlane16_swap_b32_e32 v157, v159
	global_store_dwordx4 v211, v[156:159], s[6:7] offset:256
	s_waitcnt vmcnt(24)
	v_permlane16_swap_b32_e32 v192, v194
	v_permlane16_swap_b32_e32 v193, v195
	v_lshlrev_b32_e32 v156, 16, v188
	v_and_b32_e32 v157, 0xffff0000, v188
	v_lshlrev_b32_e32 v158, 16, v189
	v_and_b32_e32 v159, 0xffff0000, v189
	v_pk_mul_f32 v[156:157], v[76:77], v[156:157]
	v_pk_mul_f32 v[158:159], v[78:79], v[158:159]
	v_permlane32_swap_b32_e32 v192, v194
	v_permlane32_swap_b32_e32 v193, v195
	v_lshlrev_b32_e32 v244, 16, v190
	v_and_b32_e32 v245, 0xffff0000, v190
	v_lshlrev_b32_e32 v246, 16, v191
	v_and_b32_e32 v247, 0xffff0000, v191
	v_pk_mul_f32 v[244:245], v[72:73], v[244:245]
	v_pk_mul_f32 v[246:247], v[74:75], v[246:247]
	v_lshlrev_b32_e32 v196, 16, v192
	v_and_b32_e32 v197, 0xffff0000, v192
	v_lshlrev_b32_e32 v198, 16, v193
	v_and_b32_e32 v199, 0xffff0000, v193
	v_pk_add_f32 v[156:157], v[156:157], v[196:197]
	v_pk_add_f32 v[158:159], v[158:159], v[198:199]
	v_lshlrev_b32_e32 v200, 16, v194
	v_and_b32_e32 v201, 0xffff0000, v194
	v_lshlrev_b32_e32 v204, 16, v195
	v_and_b32_e32 v205, 0xffff0000, v195
	v_pk_add_f32 v[244:245], v[244:245], v[200:201]
	v_pk_add_f32 v[246:247], v[246:247], v[204:205]
	v_cvt_pk_bf16_f32 v156, v156, v157
	v_cvt_pk_bf16_f32 v157, v158, v159
	v_cvt_pk_bf16_f32 v158, v244, v245
	v_cvt_pk_bf16_f32 v159, v246, v247
	v_add_u32_e32 v210, 0x20000, v163
	s_nop 1
	v_permlane32_swap_b32_e32 v156, v158
	v_permlane32_swap_b32_e32 v157, v159
	s_nop 0
	v_permlane16_swap_b32_e32 v156, v158
	v_permlane16_swap_b32_e32 v157, v159
	global_store_dwordx4 v210, v[156:159], s[6:7] offset:256
	s_waitcnt vmcnt(23)
	v_permlane16_swap_b32_e32 v216, v218
	v_permlane16_swap_b32_e32 v217, v219
	v_lshlrev_b32_e32 v156, 16, v212
	v_and_b32_e32 v157, 0xffff0000, v212
	v_lshlrev_b32_e32 v158, 16, v213
	v_and_b32_e32 v159, 0xffff0000, v213
	v_pk_mul_f32 v[156:157], v[68:69], v[156:157]
	v_pk_mul_f32 v[158:159], v[70:71], v[158:159]
	v_permlane32_swap_b32_e32 v216, v218
	v_permlane32_swap_b32_e32 v217, v219
	v_lshlrev_b32_e32 v244, 16, v214
	v_and_b32_e32 v245, 0xffff0000, v214
	v_lshlrev_b32_e32 v246, 16, v215
	v_and_b32_e32 v247, 0xffff0000, v215
	v_pk_mul_f32 v[244:245], v[64:65], v[244:245]
	v_pk_mul_f32 v[246:247], v[66:67], v[246:247]
	v_lshlrev_b32_e32 v196, 16, v216
	v_and_b32_e32 v197, 0xffff0000, v216
	v_lshlrev_b32_e32 v198, 16, v217
	v_and_b32_e32 v199, 0xffff0000, v217
	v_pk_add_f32 v[156:157], v[156:157], v[196:197]
	v_pk_add_f32 v[158:159], v[158:159], v[198:199]
	v_lshlrev_b32_e32 v200, 16, v218
	v_and_b32_e32 v201, 0xffff0000, v218
	v_lshlrev_b32_e32 v204, 16, v219
	v_and_b32_e32 v205, 0xffff0000, v219
	v_pk_add_f32 v[244:245], v[244:245], v[200:201]
	v_pk_add_f32 v[246:247], v[246:247], v[204:205]
	v_cvt_pk_bf16_f32 v156, v156, v157
	v_cvt_pk_bf16_f32 v157, v158, v159
	v_cvt_pk_bf16_f32 v158, v244, v245
	v_cvt_pk_bf16_f32 v159, v246, v247
	v_add_u32_e32 v211, 0x30000, v163
	s_nop 1
	v_permlane32_swap_b32_e32 v156, v158
	v_permlane32_swap_b32_e32 v157, v159
	s_nop 0
	v_permlane16_swap_b32_e32 v156, v158
	v_permlane16_swap_b32_e32 v157, v159
	global_store_dwordx4 v211, v[156:159], s[6:7] offset:256
	s_waitcnt vmcnt(22)
	v_permlane16_swap_b32_e32 v224, v226
	v_permlane16_swap_b32_e32 v225, v227
	v_lshlrev_b32_e32 v156, 16, v220
	v_and_b32_e32 v157, 0xffff0000, v220
	v_lshlrev_b32_e32 v158, 16, v221
	v_and_b32_e32 v159, 0xffff0000, v221
	v_pk_mul_f32 v[156:157], v[60:61], v[156:157]
	v_pk_mul_f32 v[158:159], v[62:63], v[158:159]
	v_permlane32_swap_b32_e32 v224, v226
	v_permlane32_swap_b32_e32 v225, v227
	v_lshlrev_b32_e32 v244, 16, v222
	v_and_b32_e32 v245, 0xffff0000, v222
	v_lshlrev_b32_e32 v246, 16, v223
	v_and_b32_e32 v247, 0xffff0000, v223
	v_pk_mul_f32 v[244:245], v[56:57], v[244:245]
	v_pk_mul_f32 v[246:247], v[58:59], v[246:247]
	v_lshlrev_b32_e32 v196, 16, v224
	v_and_b32_e32 v197, 0xffff0000, v224
	v_lshlrev_b32_e32 v198, 16, v225
	v_and_b32_e32 v199, 0xffff0000, v225
	v_pk_add_f32 v[156:157], v[156:157], v[196:197]
	v_pk_add_f32 v[158:159], v[158:159], v[198:199]
	v_lshlrev_b32_e32 v200, 16, v226
	v_and_b32_e32 v201, 0xffff0000, v226
	v_lshlrev_b32_e32 v204, 16, v227
	v_and_b32_e32 v205, 0xffff0000, v227
	v_pk_add_f32 v[244:245], v[244:245], v[200:201]
	v_pk_add_f32 v[246:247], v[246:247], v[204:205]
	v_cvt_pk_bf16_f32 v156, v156, v157
	v_cvt_pk_bf16_f32 v157, v158, v159
	v_cvt_pk_bf16_f32 v158, v244, v245
	v_cvt_pk_bf16_f32 v159, v246, v247
	v_add_u32_e32 v210, 0x80000, v163
	s_nop 1
	v_permlane32_swap_b32_e32 v156, v158
	v_permlane32_swap_b32_e32 v157, v159
	s_nop 0
	v_permlane16_swap_b32_e32 v156, v158
	v_permlane16_swap_b32_e32 v157, v159
	global_store_dwordx4 v210, v[156:159], s[6:7]
	s_waitcnt vmcnt(21)
; __device__ __forceinline__ float bflo(unsigned u) { return __uint_as_float(u << 16); }
; __device__ __forceinline__ float bfhi(unsigned u) { return __uint_as_float(u & 0xFFFF0000u); }
; __device__ __forceinline__ void phaseE(const Params& p, int layer) {
;     ...
;               uint4 g4[2]; uint2 old[2][2];
; #pragma unroll
;               for (int mm = 0; mm < 2; mm++) {
;                 const int m = mh * 2 + mm;
;                 g4[mm] = *(const uint4*)(gsb + ((ai * 2 + bj) * 4 + m) * 8192 + gs_lane);
;                 if (br) {
; #pragma unroll
;                   for (int n = 0; n < 2; n++)
;                     old[mm][n] = *(const uint2*)(mb + ((size_t)(ai * 128 + m * 16) * 2048 + bj * 128 + n * 16) * 2 + lane_m);
;                 }
;               }
; #pragma unroll
;               for (int mm = 0; mm < 2; mm++) {
;                 const int m = mh * 2 + mm;
;                 const unsigned gq[4] = {g4[mm].x, g4[mm].y, g4[mm].z, g4[mm].w};
; #pragma unroll
;                 for (int n = 0; n < 2; n++) {
;                   f32x4 v = acc[ai][bj][m][n];
;                   float o0 = bflo(gq[2 * n]) * v[0], o1 = bfhi(gq[2 * n]) * v[1], o2 = bflo(gq[2 * n + 1]) * v[2], o3 = bfhi(gq[2 * n + 1]) * v[3];
;                   char* mp = mb + ((size_t)(ai * 128 + m * 16) * 2048 + bj * 128 + n * 16) * 2 + lane_m;
;                   if (br) { o0 += bflo(old[mm][n].x); o1 += bfhi(old[mm][n].x); o2 += bflo(old[mm][n].y); o3 += bfhi(old[mm][n].y); }
;                   *(uint2*)mp = make_uint2(pk2(o0, o1), pk2(o2, o3));
;                 }
;               }
	v_permlane16_swap_b32_e32 v232, v234
	v_permlane16_swap_b32_e32 v233, v235
	v_lshlrev_b32_e32 v156, 16, v228
	v_and_b32_e32 v157, 0xffff0000, v228
	v_lshlrev_b32_e32 v158, 16, v229
	v_and_b32_e32 v159, 0xffff0000, v229
	v_pk_mul_f32 v[156:157], v[52:53], v[156:157]
	v_pk_mul_f32 v[158:159], v[54:55], v[158:159]
	v_permlane32_swap_b32_e32 v232, v234
	v_permlane32_swap_b32_e32 v233, v235
	v_lshlrev_b32_e32 v244, 16, v230
	v_and_b32_e32 v245, 0xffff0000, v230
	v_lshlrev_b32_e32 v246, 16, v231
	v_and_b32_e32 v247, 0xffff0000, v231
	v_pk_mul_f32 v[244:245], v[48:49], v[244:245]
	v_pk_mul_f32 v[246:247], v[50:51], v[246:247]
	v_lshlrev_b32_e32 v196, 16, v232
	v_and_b32_e32 v197, 0xffff0000, v232
	v_lshlrev_b32_e32 v198, 16, v233
	v_and_b32_e32 v199, 0xffff0000, v233
	v_pk_add_f32 v[156:157], v[156:157], v[196:197]
	v_pk_add_f32 v[158:159], v[158:159], v[198:199]
	v_lshlrev_b32_e32 v200, 16, v234
	v_and_b32_e32 v201, 0xffff0000, v234
	v_lshlrev_b32_e32 v204, 16, v235
	v_and_b32_e32 v205, 0xffff0000, v235
	v_pk_add_f32 v[244:245], v[244:245], v[200:201]
	v_pk_add_f32 v[246:247], v[246:247], v[204:205]
	v_cvt_pk_bf16_f32 v156, v156, v157
	v_cvt_pk_bf16_f32 v157, v158, v159
	v_cvt_pk_bf16_f32 v158, v244, v245
	v_cvt_pk_bf16_f32 v159, v246, v247
	v_add_u32_e32 v211, 0x90000, v163
	s_nop 1
	v_permlane32_swap_b32_e32 v156, v158
	v_permlane32_swap_b32_e32 v157, v159
	s_nop 0
	v_permlane16_swap_b32_e32 v156, v158
	v_permlane16_swap_b32_e32 v157, v159
	global_store_dwordx4 v211, v[156:159], s[6:7]
	s_waitcnt vmcnt(20)
	v_permlane16_swap_b32_e32 v240, v242
	v_permlane16_swap_b32_e32 v241, v243
	v_lshlrev_b32_e32 v156, 16, v236
	v_and_b32_e32 v157, 0xffff0000, v236
	v_lshlrev_b32_e32 v158, 16, v237
	v_and_b32_e32 v159, 0xffff0000, v237
	v_pk_mul_f32 v[156:157], v[44:45], v[156:157]
	v_pk_mul_f32 v[158:159], v[46:47], v[158:159]
	v_permlane32_swap_b32_e32 v240, v242
	v_permlane32_swap_b32_e32 v241, v243
	v_lshlrev_b32_e32 v244, 16, v238
	v_and_b32_e32 v245, 0xffff0000, v238
	v_lshlrev_b32_e32 v246, 16, v239
	v_and_b32_e32 v247, 0xffff0000, v239
	v_pk_mul_f32 v[244:245], v[40:41], v[244:245]
	v_pk_mul_f32 v[246:247], v[42:43], v[246:247]
	v_lshlrev_b32_e32 v196, 16, v240
	v_and_b32_e32 v197, 0xffff0000, v240
	v_lshlrev_b32_e32 v198, 16, v241
	v_and_b32_e32 v199, 0xffff0000, v241
	v_pk_add_f32 v[156:157], v[156:157], v[196:197]
	v_pk_add_f32 v[158:159], v[158:159], v[198:199]
	v_lshlrev_b32_e32 v200, 16, v242
	v_and_b32_e32 v201, 0xffff0000, v242
	v_lshlrev_b32_e32 v204, 16, v243
	v_and_b32_e32 v205, 0xffff0000, v243
	v_pk_add_f32 v[244:245], v[244:245], v[200:201]
	v_pk_add_f32 v[246:247], v[246:247], v[204:205]
	v_cvt_pk_bf16_f32 v156, v156, v157
	v_cvt_pk_bf16_f32 v157, v158, v159
	v_cvt_pk_bf16_f32 v158, v244, v245
	v_cvt_pk_bf16_f32 v159, v246, v247
	v_add_u32_e32 v210, 0xa0000, v163
	s_nop 1
	v_permlane32_swap_b32_e32 v156, v158
	v_permlane32_swap_b32_e32 v157, v159
	s_nop 0
	v_permlane16_swap_b32_e32 v156, v158
	v_permlane16_swap_b32_e32 v157, v159
	global_store_dwordx4 v210, v[156:159], s[6:7]
	s_waitcnt vmcnt(18)
	v_permlane16_swap_b32_e32 v132, v134
	v_permlane16_swap_b32_e32 v133, v135
	v_lshlrev_b32_e32 v156, 16, v128
	v_and_b32_e32 v157, 0xffff0000, v128
	v_lshlrev_b32_e32 v158, 16, v129
	v_and_b32_e32 v159, 0xffff0000, v129
	v_pk_mul_f32 v[156:157], v[36:37], v[156:157]
	v_pk_mul_f32 v[158:159], v[38:39], v[158:159]
	v_permlane32_swap_b32_e32 v132, v134
	v_permlane32_swap_b32_e32 v133, v135
	v_lshlrev_b32_e32 v244, 16, v130
	v_and_b32_e32 v245, 0xffff0000, v130
	v_lshlrev_b32_e32 v246, 16, v131
	v_and_b32_e32 v247, 0xffff0000, v131
	v_pk_mul_f32 v[244:245], v[32:33], v[244:245]
	v_pk_mul_f32 v[246:247], v[34:35], v[246:247]
	v_lshlrev_b32_e32 v196, 16, v132
	v_and_b32_e32 v197, 0xffff0000, v132
	v_lshlrev_b32_e32 v198, 16, v133
	v_and_b32_e32 v199, 0xffff0000, v133
	v_pk_add_f32 v[156:157], v[156:157], v[196:197]
	v_pk_add_f32 v[158:159], v[158:159], v[198:199]
	v_lshlrev_b32_e32 v200, 16, v134
	v_and_b32_e32 v201, 0xffff0000, v134
	v_lshlrev_b32_e32 v204, 16, v135
	v_and_b32_e32 v205, 0xffff0000, v135
	v_pk_add_f32 v[244:245], v[244:245], v[200:201]
	v_pk_add_f32 v[246:247], v[246:247], v[204:205]
	v_cvt_pk_bf16_f32 v156, v156, v157
	v_cvt_pk_bf16_f32 v157, v158, v159
	v_cvt_pk_bf16_f32 v158, v244, v245
	v_cvt_pk_bf16_f32 v159, v246, v247
	v_add_u32_e32 v211, 0xb0000, v163
	s_nop 1
	v_permlane32_swap_b32_e32 v156, v158
	v_permlane32_swap_b32_e32 v157, v159
	s_nop 0
	v_permlane16_swap_b32_e32 v156, v158
	v_permlane16_swap_b32_e32 v157, v159
	global_store_dwordx4 v211, v[156:159], s[6:7]
	s_waitcnt vmcnt(16)
	v_permlane16_swap_b32_e32 v140, v142
	v_permlane16_swap_b32_e32 v141, v143
	v_lshlrev_b32_e32 v156, 16, v136
	v_and_b32_e32 v157, 0xffff0000, v136
	v_lshlrev_b32_e32 v158, 16, v137
	v_and_b32_e32 v159, 0xffff0000, v137
	v_pk_mul_f32 v[156:157], v[28:29], v[156:157]
	v_pk_mul_f32 v[158:159], v[30:31], v[158:159]
	v_permlane32_swap_b32_e32 v140, v142
	v_permlane32_swap_b32_e32 v141, v143
	v_lshlrev_b32_e32 v244, 16, v138
	v_and_b32_e32 v245, 0xffff0000, v138
	v_lshlrev_b32_e32 v246, 16, v139
	v_and_b32_e32 v247, 0xffff0000, v139
	v_pk_mul_f32 v[244:245], v[24:25], v[244:245]
	v_pk_mul_f32 v[246:247], v[26:27], v[246:247]
	v_lshlrev_b32_e32 v196, 16, v140
	v_and_b32_e32 v197, 0xffff0000, v140
	v_lshlrev_b32_e32 v198, 16, v141
	v_and_b32_e32 v199, 0xffff0000, v141
	v_pk_add_f32 v[156:157], v[156:157], v[196:197]
	v_pk_add_f32 v[158:159], v[158:159], v[198:199]
	v_lshlrev_b32_e32 v200, 16, v142
	v_and_b32_e32 v201, 0xffff0000, v142
	v_lshlrev_b32_e32 v204, 16, v143
	v_and_b32_e32 v205, 0xffff0000, v143
	v_pk_add_f32 v[244:245], v[244:245], v[200:201]
	v_pk_add_f32 v[246:247], v[246:247], v[204:205]
	v_cvt_pk_bf16_f32 v156, v156, v157
	v_cvt_pk_bf16_f32 v157, v158, v159
	v_cvt_pk_bf16_f32 v158, v244, v245
	v_cvt_pk_bf16_f32 v159, v246, v247
	v_add_u32_e32 v210, 0x80000, v163
	s_nop 1
	v_permlane32_swap_b32_e32 v156, v158
	v_permlane32_swap_b32_e32 v157, v159
	s_nop 0
	v_permlane16_swap_b32_e32 v156, v158
	v_permlane16_swap_b32_e32 v157, v159
	global_store_dwordx4 v210, v[156:159], s[6:7] offset:256
	s_waitcnt vmcnt(14)
; __device__ __forceinline__ float bflo(unsigned u) { return __uint_as_float(u << 16); }
; __device__ __forceinline__ float bfhi(unsigned u) { return __uint_as_float(u & 0xFFFF0000u); }
; __device__ __forceinline__ void phaseE(const Params& p, int layer) {
;     ...
;               uint4 g4[2]; uint2 old[2][2];
; #pragma unroll
;               for (int mm = 0; mm < 2; mm++) {
;                 const int m = mh * 2 + mm;
;                 g4[mm] = *(const uint4*)(gsb + ((ai * 2 + bj) * 4 + m) * 8192 + gs_lane);
;                 if (br) {
; #pragma unroll
;                   for (int n = 0; n < 2; n++)
;                     old[mm][n] = *(const uint2*)(mb + ((size_t)(ai * 128 + m * 16) * 2048 + bj * 128 + n * 16) * 2 + lane_m);
;                 }
;               }
; #pragma unroll
;               for (int mm = 0; mm < 2; mm++) {
;                 const int m = mh * 2 + mm;
;                 const unsigned gq[4] = {g4[mm].x, g4[mm].y, g4[mm].z, g4[mm].w};
; #pragma unroll
;                 for (int n = 0; n < 2; n++) {
;                   f32x4 v = acc[ai][bj][m][n];
;                   float o0 = bflo(gq[2 * n]) * v[0], o1 = bfhi(gq[2 * n]) * v[1], o2 = bflo(gq[2 * n + 1]) * v[2], o3 = bfhi(gq[2 * n + 1]) * v[3];
;                   char* mp = mb + ((size_t)(ai * 128 + m * 16) * 2048 + bj * 128 + n * 16) * 2 + lane_m;
;                   if (br) { o0 += bflo(old[mm][n].x); o1 += bfhi(old[mm][n].x); o2 += bflo(old[mm][n].y); o3 += bfhi(old[mm][n].y); }
;                   *(uint2*)mp = make_uint2(pk2(o0, o1), pk2(o2, o3));
;                 }
;               }
	v_permlane16_swap_b32_e32 v152, v154
	v_permlane16_swap_b32_e32 v153, v155
	v_lshlrev_b32_e32 v156, 16, v148
	v_and_b32_e32 v157, 0xffff0000, v148
	v_lshlrev_b32_e32 v158, 16, v149
	v_and_b32_e32 v159, 0xffff0000, v149
	v_pk_mul_f32 v[156:157], v[20:21], v[156:157]
	v_pk_mul_f32 v[158:159], v[22:23], v[158:159]
	v_permlane32_swap_b32_e32 v152, v154
	v_permlane32_swap_b32_e32 v153, v155
	v_lshlrev_b32_e32 v244, 16, v150
	v_and_b32_e32 v245, 0xffff0000, v150
	v_lshlrev_b32_e32 v246, 16, v151
	v_and_b32_e32 v247, 0xffff0000, v151
	v_pk_mul_f32 v[244:245], v[16:17], v[244:245]
	v_pk_mul_f32 v[246:247], v[18:19], v[246:247]
	v_lshlrev_b32_e32 v196, 16, v152
	v_and_b32_e32 v197, 0xffff0000, v152
	v_lshlrev_b32_e32 v198, 16, v153
	v_and_b32_e32 v199, 0xffff0000, v153
	v_pk_add_f32 v[156:157], v[156:157], v[196:197]
	v_pk_add_f32 v[158:159], v[158:159], v[198:199]
	v_lshlrev_b32_e32 v200, 16, v154
	v_and_b32_e32 v201, 0xffff0000, v154
	v_lshlrev_b32_e32 v204, 16, v155
	v_and_b32_e32 v205, 0xffff0000, v155
	v_pk_add_f32 v[244:245], v[244:245], v[200:201]
	v_pk_add_f32 v[246:247], v[246:247], v[204:205]
	v_cvt_pk_bf16_f32 v156, v156, v157
	v_cvt_pk_bf16_f32 v157, v158, v159
	v_cvt_pk_bf16_f32 v158, v244, v245
	v_cvt_pk_bf16_f32 v159, v246, v247
	v_add_u32_e32 v211, 0x90000, v163
	s_nop 1
	v_permlane32_swap_b32_e32 v156, v158
	v_permlane32_swap_b32_e32 v157, v159
	s_nop 0
	v_permlane16_swap_b32_e32 v156, v158
	v_permlane16_swap_b32_e32 v157, v159
	global_store_dwordx4 v211, v[156:159], s[6:7] offset:256
	s_waitcnt vmcnt(12)
	v_permlane16_swap_b32_e32 v168, v170
	v_permlane16_swap_b32_e32 v169, v171
	v_lshlrev_b32_e32 v156, 16, v164
	v_and_b32_e32 v157, 0xffff0000, v164
	v_lshlrev_b32_e32 v158, 16, v165
	v_and_b32_e32 v159, 0xffff0000, v165
	v_pk_mul_f32 v[156:157], v[12:13], v[156:157]
	v_pk_mul_f32 v[158:159], v[14:15], v[158:159]
	v_permlane32_swap_b32_e32 v168, v170
	v_permlane32_swap_b32_e32 v169, v171
	v_lshlrev_b32_e32 v244, 16, v166
	v_and_b32_e32 v245, 0xffff0000, v166
	v_lshlrev_b32_e32 v246, 16, v167
	v_and_b32_e32 v247, 0xffff0000, v167
	v_pk_mul_f32 v[244:245], v[8:9], v[244:245]
	v_pk_mul_f32 v[246:247], v[10:11], v[246:247]
	v_lshlrev_b32_e32 v196, 16, v168
	v_and_b32_e32 v197, 0xffff0000, v168
	v_lshlrev_b32_e32 v198, 16, v169
	v_and_b32_e32 v199, 0xffff0000, v169
	v_pk_add_f32 v[156:157], v[156:157], v[196:197]
	v_pk_add_f32 v[158:159], v[158:159], v[198:199]
	v_lshlrev_b32_e32 v200, 16, v170
	v_and_b32_e32 v201, 0xffff0000, v170
	v_lshlrev_b32_e32 v204, 16, v171
	v_and_b32_e32 v205, 0xffff0000, v171
	v_pk_add_f32 v[244:245], v[244:245], v[200:201]
	v_pk_add_f32 v[246:247], v[246:247], v[204:205]
	v_cvt_pk_bf16_f32 v156, v156, v157
	v_cvt_pk_bf16_f32 v157, v158, v159
	v_cvt_pk_bf16_f32 v158, v244, v245
	v_cvt_pk_bf16_f32 v159, v246, v247
	v_add_u32_e32 v210, 0xa0000, v163
	s_nop 1
	v_permlane32_swap_b32_e32 v156, v158
	v_permlane32_swap_b32_e32 v157, v159
	s_nop 0
	v_permlane16_swap_b32_e32 v156, v158
	v_permlane16_swap_b32_e32 v157, v159
	global_store_dwordx4 v210, v[156:159], s[6:7] offset:256
	s_waitcnt vmcnt(10)
	v_permlane16_swap_b32_e32 v176, v178
	v_permlane16_swap_b32_e32 v177, v179
	v_lshlrev_b32_e32 v156, 16, v172
	v_and_b32_e32 v157, 0xffff0000, v172
	v_lshlrev_b32_e32 v158, 16, v173
	v_and_b32_e32 v159, 0xffff0000, v173
	v_pk_mul_f32 v[156:157], v[4:5], v[156:157]
	v_pk_mul_f32 v[158:159], v[6:7], v[158:159]
	v_permlane32_swap_b32_e32 v176, v178
	v_permlane32_swap_b32_e32 v177, v179
	v_lshlrev_b32_e32 v244, 16, v174
	v_and_b32_e32 v245, 0xffff0000, v174
	v_lshlrev_b32_e32 v246, 16, v175
	v_and_b32_e32 v247, 0xffff0000, v175
	v_pk_mul_f32 v[244:245], v[0:1], v[244:245]
	v_pk_mul_f32 v[246:247], v[2:3], v[246:247]
	v_lshlrev_b32_e32 v196, 16, v176
	v_and_b32_e32 v197, 0xffff0000, v176
	v_lshlrev_b32_e32 v198, 16, v177
	v_and_b32_e32 v199, 0xffff0000, v177
	v_pk_add_f32 v[156:157], v[156:157], v[196:197]
	v_pk_add_f32 v[158:159], v[158:159], v[198:199]
	v_lshlrev_b32_e32 v200, 16, v178
	v_and_b32_e32 v201, 0xffff0000, v178
	v_lshlrev_b32_e32 v204, 16, v179
	v_and_b32_e32 v205, 0xffff0000, v179
	v_pk_add_f32 v[244:245], v[244:245], v[200:201]
	v_pk_add_f32 v[246:247], v[246:247], v[204:205]
	v_cvt_pk_bf16_f32 v156, v156, v157
	v_cvt_pk_bf16_f32 v157, v158, v159
	v_cvt_pk_bf16_f32 v158, v244, v245
	v_cvt_pk_bf16_f32 v159, v246, v247
	v_add_u32_e32 v211, 0xb0000, v163
	s_nop 1
	v_permlane32_swap_b32_e32 v156, v158
	v_permlane32_swap_b32_e32 v157, v159
	s_nop 0
	v_permlane16_swap_b32_e32 v156, v158
	v_permlane16_swap_b32_e32 v157, v159
	global_store_dwordx4 v211, v[156:159], s[6:7] offset:256
	s_branch .LBB0_2313
; __device__ __forceinline__ float bflo(unsigned u) { return __uint_as_float(u << 16); }
; __device__ __forceinline__ float bfhi(unsigned u) { return __uint_as_float(u & 0xFFFF0000u); }
; __device__ __forceinline__ void phaseE(const Params& p, int layer) {
;     ...
;               uint4 g4[2]; uint2 old[2][2];
; #pragma unroll
;               for (int mm = 0; mm < 2; mm++) {
;                 const int m = mh * 2 + mm;
;                 g4[mm] = *(const uint4*)(gsb + ((ai * 2 + bj) * 4 + m) * 8192 + gs_lane);
;                 if (br) {
; #pragma unroll
;                   for (int n = 0; n < 2; n++)
;                     old[mm][n] = *(const uint2*)(mb + ((size_t)(ai * 128 + m * 16) * 2048 + bj * 128 + n * 16) * 2 + lane_m);
;                 }
;               }
; #pragma unroll
;               for (int mm = 0; mm < 2; mm++) {
;                 const int m = mh * 2 + mm;
;                 const unsigned gq[4] = {g4[mm].x, g4[mm].y, g4[mm].z, g4[mm].w};
; #pragma unroll
;                 for (int n = 0; n < 2; n++) {
;                   f32x4 v = acc[ai][bj][m][n];
;                   float o0 = bflo(gq[2 * n]) * v[0], o1 = bfhi(gq[2 * n]) * v[1], o2 = bflo(gq[2 * n + 1]) * v[2], o3 = bfhi(gq[2 * n + 1]) * v[3];
;                   char* mp = mb + ((size_t)(ai * 128 + m * 16) * 2048 + bj * 128 + n * 16) * 2 + lane_m;
;                   if (br) { o0 += bflo(old[mm][n].x); o1 += bfhi(old[mm][n].x); o2 += bflo(old[mm][n].y); o3 += bfhi(old[mm][n].y); }
;                   *(uint2*)mp = make_uint2(pk2(o0, o1), pk2(o2, o3));
;                 }
;               }
.Lbrepi_first:
	ds_read_b128 v[128:131], v165
	ds_read_b128 v[136:139], v165 offset:8192
	ds_read_b128 v[148:151], v165 offset:16384
	ds_read_b128 v[164:167], v165 offset:24576
	v_add_u32_e32 v146, 0x8000, v160
	global_load_dwordx4 v[172:175], v146, s[0:1]
	v_add_u32_e32 v147, 0xa000, v160
	global_load_dwordx4 v[180:183], v147, s[0:1]
	v_add_u32_e32 v146, 0xc000, v160
	global_load_dwordx4 v[188:191], v146, s[0:1]
	v_add_u32_e32 v147, 0xe000, v160
	global_load_dwordx4 v[212:215], v147, s[0:1]
	v_add_u32_e32 v146, 0x10000, v160
	global_load_dwordx4 v[220:223], v146, s[0:1]
	v_add_u32_e32 v147, 0x12000, v160
	global_load_dwordx4 v[228:231], v147, s[0:1]
	v_add_u32_e32 v146, 0x14000, v160
	global_load_dwordx4 v[236:239], v146, s[0:1]
	s_waitcnt lgkmcnt(0)
	v_lshlrev_b32_e32 v156, 16, v128
	v_and_b32_e32 v157, 0xffff0000, v128
	v_lshlrev_b32_e32 v158, 16, v129
	v_and_b32_e32 v159, 0xffff0000, v129
	v_pk_mul_f32 v[156:157], v[124:125], v[156:157]
	v_pk_mul_f32 v[158:159], v[126:127], v[158:159]
	v_lshlrev_b32_e32 v244, 16, v130
	v_and_b32_e32 v245, 0xffff0000, v130
	v_lshlrev_b32_e32 v246, 16, v131
	v_and_b32_e32 v247, 0xffff0000, v131
	v_pk_mul_f32 v[244:245], v[120:121], v[244:245]
	v_pk_mul_f32 v[246:247], v[122:123], v[246:247]
	v_cvt_pk_bf16_f32 v156, v156, v157
	v_cvt_pk_bf16_f32 v157, v158, v159
	v_cvt_pk_bf16_f32 v158, v244, v245
	v_cvt_pk_bf16_f32 v159, v246, v247
	s_nop 1
	v_permlane32_swap_b32_e32 v156, v158
	v_permlane32_swap_b32_e32 v157, v159
	s_nop 0
	v_permlane16_swap_b32_e32 v156, v158
	v_permlane16_swap_b32_e32 v157, v159
	global_store_dwordx4 v163, v[156:159], s[6:7]
	v_add_u32_e32 v147, 0x16000, v160
	global_load_dwordx4 v[128:131], v147, s[0:1]
	s_waitcnt lgkmcnt(0)
	v_lshlrev_b32_e32 v156, 16, v136
	v_and_b32_e32 v157, 0xffff0000, v136
	v_lshlrev_b32_e32 v158, 16, v137
	v_and_b32_e32 v159, 0xffff0000, v137
	v_pk_mul_f32 v[156:157], v[116:117], v[156:157]
	v_pk_mul_f32 v[158:159], v[118:119], v[158:159]
	v_lshlrev_b32_e32 v244, 16, v138
	v_and_b32_e32 v245, 0xffff0000, v138
	v_lshlrev_b32_e32 v246, 16, v139
	v_and_b32_e32 v247, 0xffff0000, v139
	v_pk_mul_f32 v[244:245], v[112:113], v[244:245]
	v_pk_mul_f32 v[246:247], v[114:115], v[246:247]
	v_cvt_pk_bf16_f32 v156, v156, v157
	v_cvt_pk_bf16_f32 v157, v158, v159
	v_cvt_pk_bf16_f32 v158, v244, v245
	v_cvt_pk_bf16_f32 v159, v246, v247
	v_add_u32_e32 v210, 0x10000, v163
	s_nop 1
	v_permlane32_swap_b32_e32 v156, v158
	v_permlane32_swap_b32_e32 v157, v159
	s_nop 0
	v_permlane16_swap_b32_e32 v156, v158
	v_permlane16_swap_b32_e32 v157, v159
	global_store_dwordx4 v210, v[156:159], s[6:7]
	v_add_u32_e32 v146, 0x18000, v160
	global_load_dwordx4 v[136:139], v146, s[0:1]
	s_waitcnt lgkmcnt(0)
	v_lshlrev_b32_e32 v156, 16, v148
	v_and_b32_e32 v157, 0xffff0000, v148
	v_lshlrev_b32_e32 v158, 16, v149
	v_and_b32_e32 v159, 0xffff0000, v149
	v_pk_mul_f32 v[156:157], v[108:109], v[156:157]
	v_pk_mul_f32 v[158:159], v[110:111], v[158:159]
	v_lshlrev_b32_e32 v244, 16, v150
	v_and_b32_e32 v245, 0xffff0000, v150
	v_lshlrev_b32_e32 v246, 16, v151
	v_and_b32_e32 v247, 0xffff0000, v151
	v_pk_mul_f32 v[244:245], v[104:105], v[244:245]
	v_pk_mul_f32 v[246:247], v[106:107], v[246:247]
	v_cvt_pk_bf16_f32 v156, v156, v157
	v_cvt_pk_bf16_f32 v157, v158, v159
	v_cvt_pk_bf16_f32 v158, v244, v245
	v_cvt_pk_bf16_f32 v159, v246, v247
	v_add_u32_e32 v211, 0x20000, v163
	s_nop 1
	v_permlane32_swap_b32_e32 v156, v158
	v_permlane32_swap_b32_e32 v157, v159
	s_nop 0
	v_permlane16_swap_b32_e32 v156, v158
	v_permlane16_swap_b32_e32 v157, v159
	global_store_dwordx4 v211, v[156:159], s[6:7]
	v_add_u32_e32 v147, 0x1a000, v160
	global_load_dwordx4 v[148:151], v147, s[0:1]
	s_waitcnt lgkmcnt(0)
	v_lshlrev_b32_e32 v156, 16, v164
	v_and_b32_e32 v157, 0xffff0000, v164
	v_lshlrev_b32_e32 v158, 16, v165
	v_and_b32_e32 v159, 0xffff0000, v165
	v_pk_mul_f32 v[156:157], v[100:101], v[156:157]
	v_pk_mul_f32 v[158:159], v[102:103], v[158:159]
	v_lshlrev_b32_e32 v244, 16, v166
	v_and_b32_e32 v245, 0xffff0000, v166
	v_lshlrev_b32_e32 v246, 16, v167
	v_and_b32_e32 v247, 0xffff0000, v167
	v_pk_mul_f32 v[244:245], v[96:97], v[244:245]
	v_pk_mul_f32 v[246:247], v[98:99], v[246:247]
	v_cvt_pk_bf16_f32 v156, v156, v157
	v_cvt_pk_bf16_f32 v157, v158, v159
	v_cvt_pk_bf16_f32 v158, v244, v245
	v_cvt_pk_bf16_f32 v159, v246, v247
	v_add_u32_e32 v210, 0x30000, v163
	s_nop 1
	v_permlane32_swap_b32_e32 v156, v158
	v_permlane32_swap_b32_e32 v157, v159
	s_nop 0
	v_permlane16_swap_b32_e32 v156, v158
	v_permlane16_swap_b32_e32 v157, v159
	global_store_dwordx4 v210, v[156:159], s[6:7]
	v_add_u32_e32 v146, 0x1c000, v160
	global_load_dwordx4 v[164:167], v146, s[0:1]
	s_waitcnt vmcnt(14)
	v_lshlrev_b32_e32 v156, 16, v172
	v_and_b32_e32 v157, 0xffff0000, v172
	v_lshlrev_b32_e32 v158, 16, v173
	v_and_b32_e32 v159, 0xffff0000, v173
	v_pk_mul_f32 v[156:157], v[92:93], v[156:157]
	v_pk_mul_f32 v[158:159], v[94:95], v[158:159]
	v_lshlrev_b32_e32 v244, 16, v174
	v_and_b32_e32 v245, 0xffff0000, v174
	v_lshlrev_b32_e32 v246, 16, v175
	v_and_b32_e32 v247, 0xffff0000, v175
	v_pk_mul_f32 v[244:245], v[88:89], v[244:245]
	v_pk_mul_f32 v[246:247], v[90:91], v[246:247]
	v_cvt_pk_bf16_f32 v156, v156, v157
	v_cvt_pk_bf16_f32 v157, v158, v159
	v_cvt_pk_bf16_f32 v158, v244, v245
	v_cvt_pk_bf16_f32 v159, v246, v247
	s_nop 1
	v_permlane32_swap_b32_e32 v156, v158
	v_permlane32_swap_b32_e32 v157, v159
	s_nop 0
	v_permlane16_swap_b32_e32 v156, v158
	v_permlane16_swap_b32_e32 v157, v159
	global_store_dwordx4 v163, v[156:159], s[6:7] offset:256
	v_add_u32_e32 v147, 0x1e000, v160
	global_load_dwordx4 v[172:175], v147, s[0:1]
	s_waitcnt vmcnt(15)
; __device__ __forceinline__ float bflo(unsigned u) { return __uint_as_float(u << 16); }
; __device__ __forceinline__ float bfhi(unsigned u) { return __uint_as_float(u & 0xFFFF0000u); }
; __device__ __forceinline__ void phaseE(const Params& p, int layer) {
;     ...
;               uint4 g4[2]; uint2 old[2][2];
; #pragma unroll
;               for (int mm = 0; mm < 2; mm++) {
;                 const int m = mh * 2 + mm;
;                 g4[mm] = *(const uint4*)(gsb + ((ai * 2 + bj) * 4 + m) * 8192 + gs_lane);
;                 if (br) {
; #pragma unroll
;                   for (int n = 0; n < 2; n++)
;                     old[mm][n] = *(const uint2*)(mb + ((size_t)(ai * 128 + m * 16) * 2048 + bj * 128 + n * 16) * 2 + lane_m);
;                 }
;               }
; #pragma unroll
;               for (int mm = 0; mm < 2; mm++) {
;                 const int m = mh * 2 + mm;
;                 const unsigned gq[4] = {g4[mm].x, g4[mm].y, g4[mm].z, g4[mm].w};
; #pragma unroll
;                 for (int n = 0; n < 2; n++) {
;                   f32x4 v = acc[ai][bj][m][n];
;                   float o0 = bflo(gq[2 * n]) * v[0], o1 = bfhi(gq[2 * n]) * v[1], o2 = bflo(gq[2 * n + 1]) * v[2], o3 = bfhi(gq[2 * n + 1]) * v[3];
;                   char* mp = mb + ((size_t)(ai * 128 + m * 16) * 2048 + bj * 128 + n * 16) * 2 + lane_m;
;                   if (br) { o0 += bflo(old[mm][n].x); o1 += bfhi(old[mm][n].x); o2 += bflo(old[mm][n].y); o3 += bfhi(old[mm][n].y); }
;                   *(uint2*)mp = make_uint2(pk2(o0, o1), pk2(o2, o3));
;                 }
;               }
	v_lshlrev_b32_e32 v156, 16, v180
	v_and_b32_e32 v157, 0xffff0000, v180
	v_lshlrev_b32_e32 v158, 16, v181
	v_and_b32_e32 v159, 0xffff0000, v181
	v_pk_mul_f32 v[156:157], v[84:85], v[156:157]
	v_pk_mul_f32 v[158:159], v[86:87], v[158:159]
	v_lshlrev_b32_e32 v244, 16, v182
	v_and_b32_e32 v245, 0xffff0000, v182
	v_lshlrev_b32_e32 v246, 16, v183
	v_and_b32_e32 v247, 0xffff0000, v183
	v_pk_mul_f32 v[244:245], v[80:81], v[244:245]
	v_pk_mul_f32 v[246:247], v[82:83], v[246:247]
	v_cvt_pk_bf16_f32 v156, v156, v157
	v_cvt_pk_bf16_f32 v157, v158, v159
	v_cvt_pk_bf16_f32 v158, v244, v245
	v_cvt_pk_bf16_f32 v159, v246, v247
	v_add_u32_e32 v211, 0x10000, v163
	s_nop 1
	v_permlane32_swap_b32_e32 v156, v158
	v_permlane32_swap_b32_e32 v157, v159
	s_nop 0
	v_permlane16_swap_b32_e32 v156, v158
	v_permlane16_swap_b32_e32 v157, v159
	global_store_dwordx4 v211, v[156:159], s[6:7] offset:256
	s_waitcnt vmcnt(15)
	v_lshlrev_b32_e32 v156, 16, v188
	v_and_b32_e32 v157, 0xffff0000, v188
	v_lshlrev_b32_e32 v158, 16, v189
	v_and_b32_e32 v159, 0xffff0000, v189
	v_pk_mul_f32 v[156:157], v[76:77], v[156:157]
	v_pk_mul_f32 v[158:159], v[78:79], v[158:159]
	v_lshlrev_b32_e32 v244, 16, v190
	v_and_b32_e32 v245, 0xffff0000, v190
	v_lshlrev_b32_e32 v246, 16, v191
	v_and_b32_e32 v247, 0xffff0000, v191
	v_pk_mul_f32 v[244:245], v[72:73], v[244:245]
	v_pk_mul_f32 v[246:247], v[74:75], v[246:247]
	v_cvt_pk_bf16_f32 v156, v156, v157
	v_cvt_pk_bf16_f32 v157, v158, v159
	v_cvt_pk_bf16_f32 v158, v244, v245
	v_cvt_pk_bf16_f32 v159, v246, v247
	v_add_u32_e32 v210, 0x20000, v163
	s_nop 1
	v_permlane32_swap_b32_e32 v156, v158
	v_permlane32_swap_b32_e32 v157, v159
	s_nop 0
	v_permlane16_swap_b32_e32 v156, v158
	v_permlane16_swap_b32_e32 v157, v159
	global_store_dwordx4 v210, v[156:159], s[6:7] offset:256
	s_waitcnt vmcnt(15)
	v_lshlrev_b32_e32 v156, 16, v212
	v_and_b32_e32 v157, 0xffff0000, v212
	v_lshlrev_b32_e32 v158, 16, v213
	v_and_b32_e32 v159, 0xffff0000, v213
	v_pk_mul_f32 v[156:157], v[68:69], v[156:157]
	v_pk_mul_f32 v[158:159], v[70:71], v[158:159]
	v_lshlrev_b32_e32 v244, 16, v214
	v_and_b32_e32 v245, 0xffff0000, v214
	v_lshlrev_b32_e32 v246, 16, v215
	v_and_b32_e32 v247, 0xffff0000, v215
	v_pk_mul_f32 v[244:245], v[64:65], v[244:245]
	v_pk_mul_f32 v[246:247], v[66:67], v[246:247]
	v_cvt_pk_bf16_f32 v156, v156, v157
	v_cvt_pk_bf16_f32 v157, v158, v159
	v_cvt_pk_bf16_f32 v158, v244, v245
	v_cvt_pk_bf16_f32 v159, v246, v247
	v_add_u32_e32 v211, 0x30000, v163
	s_nop 1
	v_permlane32_swap_b32_e32 v156, v158
	v_permlane32_swap_b32_e32 v157, v159
	s_nop 0
	v_permlane16_swap_b32_e32 v156, v158
	v_permlane16_swap_b32_e32 v157, v159
	global_store_dwordx4 v211, v[156:159], s[6:7] offset:256
	s_waitcnt vmcnt(15)
	v_lshlrev_b32_e32 v156, 16, v220
	v_and_b32_e32 v157, 0xffff0000, v220
	v_lshlrev_b32_e32 v158, 16, v221
	v_and_b32_e32 v159, 0xffff0000, v221
	v_pk_mul_f32 v[156:157], v[60:61], v[156:157]
	v_pk_mul_f32 v[158:159], v[62:63], v[158:159]
	v_lshlrev_b32_e32 v244, 16, v222
	v_and_b32_e32 v245, 0xffff0000, v222
	v_lshlrev_b32_e32 v246, 16, v223
	v_and_b32_e32 v247, 0xffff0000, v223
	v_pk_mul_f32 v[244:245], v[56:57], v[244:245]
	v_pk_mul_f32 v[246:247], v[58:59], v[246:247]
	v_cvt_pk_bf16_f32 v156, v156, v157
	v_cvt_pk_bf16_f32 v157, v158, v159
	v_cvt_pk_bf16_f32 v158, v244, v245
	v_cvt_pk_bf16_f32 v159, v246, v247
	v_add_u32_e32 v210, 0x80000, v163
	s_nop 1
	v_permlane32_swap_b32_e32 v156, v158
	v_permlane32_swap_b32_e32 v157, v159
	s_nop 0
	v_permlane16_swap_b32_e32 v156, v158
	v_permlane16_swap_b32_e32 v157, v159
	global_store_dwordx4 v210, v[156:159], s[6:7]
	s_waitcnt vmcnt(15)
	v_lshlrev_b32_e32 v156, 16, v228
	v_and_b32_e32 v157, 0xffff0000, v228
	v_lshlrev_b32_e32 v158, 16, v229
	v_and_b32_e32 v159, 0xffff0000, v229
	v_pk_mul_f32 v[156:157], v[52:53], v[156:157]
	v_pk_mul_f32 v[158:159], v[54:55], v[158:159]
	v_lshlrev_b32_e32 v244, 16, v230
	v_and_b32_e32 v245, 0xffff0000, v230
	v_lshlrev_b32_e32 v246, 16, v231
	v_and_b32_e32 v247, 0xffff0000, v231
	v_pk_mul_f32 v[244:245], v[48:49], v[244:245]
	v_pk_mul_f32 v[246:247], v[50:51], v[246:247]
	v_cvt_pk_bf16_f32 v156, v156, v157
	v_cvt_pk_bf16_f32 v157, v158, v159
	v_cvt_pk_bf16_f32 v158, v244, v245
	v_cvt_pk_bf16_f32 v159, v246, v247
	v_add_u32_e32 v211, 0x90000, v163
	s_nop 1
	v_permlane32_swap_b32_e32 v156, v158
	v_permlane32_swap_b32_e32 v157, v159
	s_nop 0
	v_permlane16_swap_b32_e32 v156, v158
	v_permlane16_swap_b32_e32 v157, v159
	global_store_dwordx4 v211, v[156:159], s[6:7]
	s_waitcnt vmcnt(15)
	v_lshlrev_b32_e32 v156, 16, v236
	v_and_b32_e32 v157, 0xffff0000, v236
	v_lshlrev_b32_e32 v158, 16, v237
	v_and_b32_e32 v159, 0xffff0000, v237
	v_pk_mul_f32 v[156:157], v[44:45], v[156:157]
	v_pk_mul_f32 v[158:159], v[46:47], v[158:159]
	v_lshlrev_b32_e32 v244, 16, v238
	v_and_b32_e32 v245, 0xffff0000, v238
	v_lshlrev_b32_e32 v246, 16, v239
	v_and_b32_e32 v247, 0xffff0000, v239
	v_pk_mul_f32 v[244:245], v[40:41], v[244:245]
	v_pk_mul_f32 v[246:247], v[42:43], v[246:247]
	v_cvt_pk_bf16_f32 v156, v156, v157
	v_cvt_pk_bf16_f32 v157, v158, v159
	v_cvt_pk_bf16_f32 v158, v244, v245
	v_cvt_pk_bf16_f32 v159, v246, v247
	v_add_u32_e32 v210, 0xa0000, v163
	s_nop 1
	v_permlane32_swap_b32_e32 v156, v158
	v_permlane32_swap_b32_e32 v157, v159
	s_nop 0
	v_permlane16_swap_b32_e32 v156, v158
	v_permlane16_swap_b32_e32 v157, v159
	global_store_dwordx4 v210, v[156:159], s[6:7]
	s_waitcnt vmcnt(14)
; __device__ __forceinline__ float bflo(unsigned u) { return __uint_as_float(u << 16); }
; __device__ __forceinline__ float bfhi(unsigned u) { return __uint_as_float(u & 0xFFFF0000u); }
; __device__ __forceinline__ void phaseE(const Params& p, int layer) {
;     ...
;               uint4 g4[2]; uint2 old[2][2];
; #pragma unroll
;               for (int mm = 0; mm < 2; mm++) {
;                 const int m = mh * 2 + mm;
;                 g4[mm] = *(const uint4*)(gsb + ((ai * 2 + bj) * 4 + m) * 8192 + gs_lane);
;                 if (br) {
; #pragma unroll
;                   for (int n = 0; n < 2; n++)
;                     old[mm][n] = *(const uint2*)(mb + ((size_t)(ai * 128 + m * 16) * 2048 + bj * 128 + n * 16) * 2 + lane_m);
;                 }
;               }
; #pragma unroll
;               for (int mm = 0; mm < 2; mm++) {
;                 const int m = mh * 2 + mm;
;                 const unsigned gq[4] = {g4[mm].x, g4[mm].y, g4[mm].z, g4[mm].w};
; #pragma unroll
;                 for (int n = 0; n < 2; n++) {
;                   f32x4 v = acc[ai][bj][m][n];
;                   float o0 = bflo(gq[2 * n]) * v[0], o1 = bfhi(gq[2 * n]) * v[1], o2 = bflo(gq[2 * n + 1]) * v[2], o3 = bfhi(gq[2 * n + 1]) * v[3];
;                   char* mp = mb + ((size_t)(ai * 128 + m * 16) * 2048 + bj * 128 + n * 16) * 2 + lane_m;
;                   if (br) { o0 += bflo(old[mm][n].x); o1 += bfhi(old[mm][n].x); o2 += bflo(old[mm][n].y); o3 += bfhi(old[mm][n].y); }
;                   *(uint2*)mp = make_uint2(pk2(o0, o1), pk2(o2, o3));
;                 }
;               }
	v_lshlrev_b32_e32 v156, 16, v128
	v_and_b32_e32 v157, 0xffff0000, v128
	v_lshlrev_b32_e32 v158, 16, v129
	v_and_b32_e32 v159, 0xffff0000, v129
	v_pk_mul_f32 v[156:157], v[36:37], v[156:157]
	v_pk_mul_f32 v[158:159], v[38:39], v[158:159]
	v_lshlrev_b32_e32 v244, 16, v130
	v_and_b32_e32 v245, 0xffff0000, v130
	v_lshlrev_b32_e32 v246, 16, v131
	v_and_b32_e32 v247, 0xffff0000, v131
	v_pk_mul_f32 v[244:245], v[32:33], v[244:245]
	v_pk_mul_f32 v[246:247], v[34:35], v[246:247]
	v_cvt_pk_bf16_f32 v156, v156, v157
	v_cvt_pk_bf16_f32 v157, v158, v159
	v_cvt_pk_bf16_f32 v158, v244, v245
	v_cvt_pk_bf16_f32 v159, v246, v247
	v_add_u32_e32 v211, 0xb0000, v163
	s_nop 1
	v_permlane32_swap_b32_e32 v156, v158
	v_permlane32_swap_b32_e32 v157, v159
	s_nop 0
	v_permlane16_swap_b32_e32 v156, v158
	v_permlane16_swap_b32_e32 v157, v159
	global_store_dwordx4 v211, v[156:159], s[6:7]
	s_waitcnt vmcnt(13)
	v_lshlrev_b32_e32 v156, 16, v136
	v_and_b32_e32 v157, 0xffff0000, v136
	v_lshlrev_b32_e32 v158, 16, v137
	v_and_b32_e32 v159, 0xffff0000, v137
	v_pk_mul_f32 v[156:157], v[28:29], v[156:157]
	v_pk_mul_f32 v[158:159], v[30:31], v[158:159]
	v_lshlrev_b32_e32 v244, 16, v138
	v_and_b32_e32 v245, 0xffff0000, v138
	v_lshlrev_b32_e32 v246, 16, v139
	v_and_b32_e32 v247, 0xffff0000, v139
	v_pk_mul_f32 v[244:245], v[24:25], v[244:245]
	v_pk_mul_f32 v[246:247], v[26:27], v[246:247]
	v_cvt_pk_bf16_f32 v156, v156, v157
	v_cvt_pk_bf16_f32 v157, v158, v159
	v_cvt_pk_bf16_f32 v158, v244, v245
	v_cvt_pk_bf16_f32 v159, v246, v247
	v_add_u32_e32 v210, 0x80000, v163
	s_nop 1
	v_permlane32_swap_b32_e32 v156, v158
	v_permlane32_swap_b32_e32 v157, v159
	s_nop 0
	v_permlane16_swap_b32_e32 v156, v158
	v_permlane16_swap_b32_e32 v157, v159
	global_store_dwordx4 v210, v[156:159], s[6:7] offset:256
	s_waitcnt vmcnt(12)
	v_lshlrev_b32_e32 v156, 16, v148
	v_and_b32_e32 v157, 0xffff0000, v148
	v_lshlrev_b32_e32 v158, 16, v149
	v_and_b32_e32 v159, 0xffff0000, v149
	v_pk_mul_f32 v[156:157], v[20:21], v[156:157]
	v_pk_mul_f32 v[158:159], v[22:23], v[158:159]
	v_lshlrev_b32_e32 v244, 16, v150
	v_and_b32_e32 v245, 0xffff0000, v150
	v_lshlrev_b32_e32 v246, 16, v151
	v_and_b32_e32 v247, 0xffff0000, v151
	v_pk_mul_f32 v[244:245], v[16:17], v[244:245]
	v_pk_mul_f32 v[246:247], v[18:19], v[246:247]
	v_cvt_pk_bf16_f32 v156, v156, v157
	v_cvt_pk_bf16_f32 v157, v158, v159
	v_cvt_pk_bf16_f32 v158, v244, v245
	v_cvt_pk_bf16_f32 v159, v246, v247
	v_add_u32_e32 v211, 0x90000, v163
	s_nop 1
	v_permlane32_swap_b32_e32 v156, v158
	v_permlane32_swap_b32_e32 v157, v159
	s_nop 0
	v_permlane16_swap_b32_e32 v156, v158
	v_permlane16_swap_b32_e32 v157, v159
	global_store_dwordx4 v211, v[156:159], s[6:7] offset:256
	s_waitcnt vmcnt(11)
	v_lshlrev_b32_e32 v156, 16, v164
	v_and_b32_e32 v157, 0xffff0000, v164
	v_lshlrev_b32_e32 v158, 16, v165
	v_and_b32_e32 v159, 0xffff0000, v165
	v_pk_mul_f32 v[156:157], v[12:13], v[156:157]
	v_pk_mul_f32 v[158:159], v[14:15], v[158:159]
	v_lshlrev_b32_e32 v244, 16, v166
	v_and_b32_e32 v245, 0xffff0000, v166
	v_lshlrev_b32_e32 v246, 16, v167
	v_and_b32_e32 v247, 0xffff0000, v167
	v_pk_mul_f32 v[244:245], v[8:9], v[244:245]
	v_pk_mul_f32 v[246:247], v[10:11], v[246:247]
	v_cvt_pk_bf16_f32 v156, v156, v157
	v_cvt_pk_bf16_f32 v157, v158, v159
	v_cvt_pk_bf16_f32 v158, v244, v245
	v_cvt_pk_bf16_f32 v159, v246, v247
	v_add_u32_e32 v210, 0xa0000, v163
	s_nop 1
	v_permlane32_swap_b32_e32 v156, v158
	v_permlane32_swap_b32_e32 v157, v159
	s_nop 0
	v_permlane16_swap_b32_e32 v156, v158
	v_permlane16_swap_b32_e32 v157, v159
	global_store_dwordx4 v210, v[156:159], s[6:7] offset:256
	s_waitcnt vmcnt(10)
	v_lshlrev_b32_e32 v156, 16, v172
	v_and_b32_e32 v157, 0xffff0000, v172
	v_lshlrev_b32_e32 v158, 16, v173
	v_and_b32_e32 v159, 0xffff0000, v173
	v_pk_mul_f32 v[156:157], v[4:5], v[156:157]
	v_pk_mul_f32 v[158:159], v[6:7], v[158:159]
	v_lshlrev_b32_e32 v244, 16, v174
	v_and_b32_e32 v245, 0xffff0000, v174
	v_lshlrev_b32_e32 v246, 16, v175
	v_and_b32_e32 v247, 0xffff0000, v175
	v_pk_mul_f32 v[244:245], v[0:1], v[244:245]
	v_pk_mul_f32 v[246:247], v[2:3], v[246:247]
	v_cvt_pk_bf16_f32 v156, v156, v157
	v_cvt_pk_bf16_f32 v157, v158, v159
	v_cvt_pk_bf16_f32 v158, v244, v245
	v_cvt_pk_bf16_f32 v159, v246, v247
	v_add_u32_e32 v211, 0xb0000, v163
	s_nop 1
	v_permlane32_swap_b32_e32 v156, v158
	v_permlane32_swap_b32_e32 v157, v159
	s_nop 0
	v_permlane16_swap_b32_e32 v156, v158
	v_permlane16_swap_b32_e32 v157, v159
	global_store_dwordx4 v211, v[156:159], s[6:7] offset:256
	s_branch .LBB0_2313
; __device__ __forceinline__ float sigmoidf_(float x) { return __builtin_amdgcn_rcpf(1.f + __expf(-x)); }
; __device__ __forceinline__ void phaseE(const Params& p, int layer) {
;     ...
;         const char* bgb = (const char*)(p.b_gate + (size_t)layer * 8192 + br * 2048 + bcol + wc * 32);
;         float4 bgv[2][2];
; #pragma unroll
;         for (int bj = 0; bj < 2; bj++)
; #pragma unroll
;           for (int n = 0; n < 2; n++) bgv[bj][n] = *(const float4*)(bgb + (bj * 128 + n * 16) * 4 + lane_c4);
; #pragma unroll
;         for (int ai = 0; ai < 2; ai++)
; #pragma unroll
;           for (int bj = 0; bj < 2; bj++)
; #pragma unroll
;             for (int m = 0; m < 4; m++) {
;               unsigned q[4];
; #pragma unroll
;               for (int n = 0; n < 2; n++) {
;                 const float4 bg = bgv[bj][n];
;                 f32x4 v = acc[ai][bj][m][n];
;                 q[2 * n] = pk2(sigmoidf_(v[0] + bg.x), sigmoidf_(v[1] + bg.y));
;                 q[2 * n + 1] = pk2(sigmoidf_(v[2] + bg.z), sigmoidf_(v[3] + bg.w));
;               }
;               *(uint4*)(gsb + ((ai * 2 + bj) * 4 + m) * 8192 + gs_lane) = make_uint4(q[0], q[1], q[2], q[3]);
;               __builtin_amdgcn_sched_barrier(0);
;             }
.LBB0_2420:
	s_lshl_b32 s68, s5, 11
	s_lshl_b64 s[0:1], s[68:69], 2
	s_add_u32 s0, s35, s0
	s_addc_u32 s1, s36, s1
	global_load_dwordx4 v[140:143], v163, s[0:1]
	global_load_dwordx4 v[136:139], v163, s[0:1] offset:64
	global_load_dwordx4 v[132:135], v163, s[0:1] offset:512
	global_load_dwordx4 v[128:131], v163, s[0:1] offset:576
	v_readlane_b32 s0, v253, 51
	v_readlane_b32 s1, v253, 52
	s_waitcnt vmcnt(0)
	v_add_f32_e32 v124, v124, v140
	v_add_f32_e32 v125, v125, v141
	v_add_f32_e32 v126, v126, v142
	v_add_f32_e32 v127, v127, v143
	v_add_f32_e32 v120, v120, v136
	v_add_f32_e32 v121, v121, v137
	v_add_f32_e32 v122, v122, v138
	v_add_f32_e32 v123, v123, v139
	v_mul_f32_e32 v124, 0xbfb8aa3b, v124
	v_mul_f32_e32 v125, 0xbfb8aa3b, v125
	v_mul_f32_e32 v126, 0xbfb8aa3b, v126
	v_mul_f32_e32 v127, 0xbfb8aa3b, v127
	v_mul_f32_e32 v120, 0xbfb8aa3b, v120
	v_mul_f32_e32 v121, 0xbfb8aa3b, v121
	v_mul_f32_e32 v122, 0xbfb8aa3b, v122
	v_mul_f32_e32 v123, 0xbfb8aa3b, v123
	v_exp_f32_e32 v124, v124
	v_exp_f32_e32 v125, v125
	v_exp_f32_e32 v126, v126
	v_exp_f32_e32 v127, v127
	v_exp_f32_e32 v120, v120
	v_exp_f32_e32 v121, v121
	v_exp_f32_e32 v122, v122
	v_exp_f32_e32 v123, v123
	v_add_f32_e32 v124, 1.0, v124
	v_add_f32_e32 v125, 1.0, v125
	v_add_f32_e32 v126, 1.0, v126
	v_add_f32_e32 v127, 1.0, v127
	v_add_f32_e32 v120, 1.0, v120
	v_add_f32_e32 v121, 1.0, v121
	v_add_f32_e32 v122, 1.0, v122
	v_add_f32_e32 v123, 1.0, v123
	v_rcp_f32_e32 v124, v124
	v_rcp_f32_e32 v125, v125
	v_rcp_f32_e32 v126, v126
	v_rcp_f32_e32 v127, v127
	v_rcp_f32_e32 v156, v120
	v_rcp_f32_e32 v157, v121
	v_rcp_f32_e32 v158, v122
	v_rcp_f32_e32 v123, v123
	v_cvt_pk_bf16_f32 v120, v124, v125
	v_cvt_pk_bf16_f32 v121, v126, v127
	v_cvt_pk_bf16_f32 v122, v156, v157
	v_cvt_pk_bf16_f32 v123, v158, v123
	v_lshl_add_u64 v[154:155], s[0:1], 0, v[144:145]
	v_add_u32_e32 v164, 0x20000, v160
	ds_write_b128 v164, v[120:123]
	v_add_f32_e32 v112, v112, v136
	v_mul_f32_e32 v112, 0xbfb8aa3b, v112
	v_add_f32_e32 v113, v113, v137
	v_exp_f32_e32 v112, v112
	v_mul_f32_e32 v113, 0xbfb8aa3b, v113
	v_exp_f32_e32 v113, v113
	v_add_f32_e32 v116, v116, v140
	v_add_f32_e32 v112, 1.0, v112
	v_add_f32_e32 v117, v117, v141
	v_rcp_f32_e32 v120, v112
	v_add_f32_e32 v112, 1.0, v113
	v_add_f32_e32 v113, v114, v138
	v_mul_f32_e32 v116, 0xbfb8aa3b, v116
	v_mul_f32_e32 v117, 0xbfb8aa3b, v117
	v_add_f32_e32 v118, v118, v142
	v_add_f32_e32 v119, v119, v143
	v_mul_f32_e32 v113, 0xbfb8aa3b, v113
	v_add_f32_e32 v114, v115, v139
	v_exp_f32_e32 v116, v116
	v_exp_f32_e32 v117, v117
	v_mul_f32_e32 v118, 0xbfb8aa3b, v118
	v_mul_f32_e32 v119, 0xbfb8aa3b, v119
	v_exp_f32_e32 v113, v113
	v_mul_f32_e32 v114, 0xbfb8aa3b, v114
	v_exp_f32_e32 v118, v118
	v_exp_f32_e32 v119, v119
	v_exp_f32_e32 v114, v114
	v_add_f32_e32 v116, 1.0, v116
	v_add_f32_e32 v117, 1.0, v117
	v_rcp_f32_e32 v115, v112
	v_add_f32_e32 v112, 1.0, v113
	v_rcp_f32_e32 v116, v116
	v_rcp_f32_e32 v117, v117
	v_add_f32_e32 v118, 1.0, v118
	v_add_f32_e32 v119, 1.0, v119
	v_rcp_f32_e32 v121, v112
	v_add_f32_e32 v112, 1.0, v114
	v_rcp_f32_e32 v118, v118
	v_rcp_f32_e32 v119, v119
	v_rcp_f32_e32 v122, v112
	s_movk_i32 s0, 0x2000
	v_cvt_pk_bf16_f32 v112, v116, v117
	v_add_co_u32_e32 v116, vcc, s0, v154
	v_cvt_pk_bf16_f32 v113, v118, v119
	v_cvt_pk_bf16_f32 v114, v120, v115
	v_cvt_pk_bf16_f32 v115, v121, v122
	v_addc_co_u32_e32 v117, vcc, 0, v155, vcc
	ds_write_b128 v164, v[112:115] offset:8192
	v_add_f32_e32 v104, v104, v136
	v_mul_f32_e32 v104, 0xbfb8aa3b, v104
	v_add_f32_e32 v105, v105, v137
	v_exp_f32_e32 v104, v104
	v_mul_f32_e32 v105, 0xbfb8aa3b, v105
	v_exp_f32_e32 v105, v105
	v_add_f32_e32 v108, v108, v140
	v_add_f32_e32 v104, 1.0, v104
	v_add_f32_e32 v109, v109, v141
	v_rcp_f32_e32 v112, v104
	v_add_f32_e32 v104, 1.0, v105
	v_add_f32_e32 v105, v106, v138
	v_mul_f32_e32 v108, 0xbfb8aa3b, v108
	v_mul_f32_e32 v109, 0xbfb8aa3b, v109
	v_add_f32_e32 v110, v110, v142
	v_add_f32_e32 v111, v111, v143
	v_mul_f32_e32 v105, 0xbfb8aa3b, v105
	v_add_f32_e32 v106, v107, v139
	v_exp_f32_e32 v108, v108
	v_exp_f32_e32 v109, v109
	v_mul_f32_e32 v110, 0xbfb8aa3b, v110
	v_mul_f32_e32 v111, 0xbfb8aa3b, v111
	v_exp_f32_e32 v105, v105
	v_mul_f32_e32 v106, 0xbfb8aa3b, v106
	v_exp_f32_e32 v110, v110
	v_exp_f32_e32 v111, v111
	v_exp_f32_e32 v106, v106
	v_add_f32_e32 v108, 1.0, v108
	v_add_f32_e32 v109, 1.0, v109
	v_rcp_f32_e32 v107, v104
	v_add_f32_e32 v104, 1.0, v105
	v_rcp_f32_e32 v108, v108
	v_rcp_f32_e32 v109, v109
	v_add_f32_e32 v110, 1.0, v110
	v_add_f32_e32 v111, 1.0, v111
	v_rcp_f32_e32 v113, v104
	v_add_f32_e32 v104, 1.0, v106
	v_rcp_f32_e32 v110, v110
	v_rcp_f32_e32 v111, v111
	v_rcp_f32_e32 v114, v104
	s_movk_i32 s0, 0x4000
	v_cvt_pk_bf16_f32 v104, v108, v109
	v_add_co_u32_e32 v108, vcc, s0, v154
	v_cvt_pk_bf16_f32 v105, v110, v111
	v_cvt_pk_bf16_f32 v106, v112, v107
	v_cvt_pk_bf16_f32 v107, v113, v114
	v_addc_co_u32_e32 v109, vcc, 0, v155, vcc
	ds_write_b128 v164, v[104:107] offset:16384
	v_add_f32_e32 v96, v96, v136
	v_mul_f32_e32 v96, 0xbfb8aa3b, v96
	v_add_f32_e32 v97, v97, v137
	v_exp_f32_e32 v96, v96
	v_mul_f32_e32 v97, 0xbfb8aa3b, v97
	v_exp_f32_e32 v97, v97
	v_add_f32_e32 v100, v100, v140
	v_add_f32_e32 v96, 1.0, v96
	v_add_f32_e32 v101, v101, v141
	v_rcp_f32_e32 v104, v96
	v_add_f32_e32 v96, 1.0, v97
	v_add_f32_e32 v97, v98, v138
	v_mul_f32_e32 v100, 0xbfb8aa3b, v100
	v_mul_f32_e32 v101, 0xbfb8aa3b, v101
	v_add_f32_e32 v102, v102, v142
	v_add_f32_e32 v103, v103, v143
	v_mul_f32_e32 v97, 0xbfb8aa3b, v97
	v_add_f32_e32 v98, v99, v139
	v_exp_f32_e32 v100, v100
	v_exp_f32_e32 v101, v101
	v_mul_f32_e32 v102, 0xbfb8aa3b, v102
	v_mul_f32_e32 v103, 0xbfb8aa3b, v103
	v_exp_f32_e32 v97, v97
; __device__ __forceinline__ float sigmoidf_(float x) { return __builtin_amdgcn_rcpf(1.f + __expf(-x)); }
; __device__ __forceinline__ void phaseE(const Params& p, int layer) {
;     ...
;         for (int ai = 0; ai < 2; ai++)
; #pragma unroll
;           for (int bj = 0; bj < 2; bj++)
; #pragma unroll
;             for (int m = 0; m < 4; m++) {
;               unsigned q[4];
; #pragma unroll
;               for (int n = 0; n < 2; n++) {
;                 const float4 bg = bgv[bj][n];
;                 f32x4 v = acc[ai][bj][m][n];
;                 q[2 * n] = pk2(sigmoidf_(v[0] + bg.x), sigmoidf_(v[1] + bg.y));
;                 q[2 * n + 1] = pk2(sigmoidf_(v[2] + bg.z), sigmoidf_(v[3] + bg.w));
;               }
;               *(uint4*)(gsb + ((ai * 2 + bj) * 4 + m) * 8192 + gs_lane) = make_uint4(q[0], q[1], q[2], q[3]);
;               __builtin_amdgcn_sched_barrier(0);
;             }
	v_mul_f32_e32 v98, 0xbfb8aa3b, v98
	v_exp_f32_e32 v102, v102
	v_exp_f32_e32 v103, v103
	v_exp_f32_e32 v98, v98
	v_add_f32_e32 v100, 1.0, v100
	v_add_f32_e32 v101, 1.0, v101
	v_rcp_f32_e32 v99, v96
	v_add_f32_e32 v96, 1.0, v97
	v_rcp_f32_e32 v100, v100
	v_rcp_f32_e32 v101, v101
	v_add_f32_e32 v102, 1.0, v102
	v_add_f32_e32 v103, 1.0, v103
	v_rcp_f32_e32 v105, v96
	v_add_f32_e32 v96, 1.0, v98
	v_rcp_f32_e32 v102, v102
	v_rcp_f32_e32 v103, v103
	v_rcp_f32_e32 v106, v96
	s_movk_i32 s0, 0x6000
	v_cvt_pk_bf16_f32 v96, v100, v101
	v_add_co_u32_e32 v100, vcc, s0, v154
	v_cvt_pk_bf16_f32 v97, v102, v103
	v_cvt_pk_bf16_f32 v98, v104, v99
	v_cvt_pk_bf16_f32 v99, v105, v106
	v_addc_co_u32_e32 v101, vcc, 0, v155, vcc
	ds_write_b128 v164, v[96:99] offset:24576
	v_add_f32_e32 v88, v88, v128
	v_mul_f32_e32 v88, 0xbfb8aa3b, v88
	v_add_f32_e32 v89, v89, v129
	v_exp_f32_e32 v88, v88
	v_mul_f32_e32 v89, 0xbfb8aa3b, v89
	v_exp_f32_e32 v89, v89
	v_add_f32_e32 v92, v92, v132
	v_add_f32_e32 v88, 1.0, v88
	v_add_f32_e32 v93, v93, v133
	v_rcp_f32_e32 v96, v88
	v_add_f32_e32 v88, 1.0, v89
	v_add_f32_e32 v89, v90, v130
	v_mul_f32_e32 v92, 0xbfb8aa3b, v92
	v_mul_f32_e32 v93, 0xbfb8aa3b, v93
	v_add_f32_e32 v94, v94, v134
	v_add_f32_e32 v95, v95, v135
	v_mul_f32_e32 v89, 0xbfb8aa3b, v89
	v_add_f32_e32 v90, v91, v131
	v_exp_f32_e32 v92, v92
	v_exp_f32_e32 v93, v93
	v_mul_f32_e32 v94, 0xbfb8aa3b, v94
	v_mul_f32_e32 v95, 0xbfb8aa3b, v95
	v_exp_f32_e32 v89, v89
	v_mul_f32_e32 v90, 0xbfb8aa3b, v90
	v_exp_f32_e32 v94, v94
	v_exp_f32_e32 v95, v95
	v_exp_f32_e32 v90, v90
	v_add_f32_e32 v92, 1.0, v92
	v_add_f32_e32 v93, 1.0, v93
	v_rcp_f32_e32 v91, v88
	v_add_f32_e32 v88, 1.0, v89
	v_rcp_f32_e32 v92, v92
	v_rcp_f32_e32 v93, v93
	v_add_f32_e32 v94, 1.0, v94
	v_add_f32_e32 v95, 1.0, v95
	v_rcp_f32_e32 v97, v88
	v_add_f32_e32 v88, 1.0, v90
	v_rcp_f32_e32 v94, v94
	v_rcp_f32_e32 v95, v95
	v_rcp_f32_e32 v98, v88
	s_mov_b32 s0, 0x8000
	v_cvt_pk_bf16_f32 v88, v92, v93
	v_add_co_u32_e32 v92, vcc, s0, v154
	v_cvt_pk_bf16_f32 v89, v94, v95
	v_cvt_pk_bf16_f32 v90, v96, v91
	v_cvt_pk_bf16_f32 v91, v97, v98
	v_addc_co_u32_e32 v93, vcc, 0, v155, vcc
	global_store_dwordx4 v[92:93], v[88:91], off
	v_add_f32_e32 v80, v80, v128
	v_mul_f32_e32 v80, 0xbfb8aa3b, v80
	v_add_f32_e32 v81, v81, v129
	v_exp_f32_e32 v80, v80
	v_mul_f32_e32 v81, 0xbfb8aa3b, v81
	v_exp_f32_e32 v81, v81
	v_add_f32_e32 v84, v84, v132
	v_add_f32_e32 v80, 1.0, v80
	v_add_f32_e32 v85, v85, v133
	v_rcp_f32_e32 v88, v80
	v_add_f32_e32 v80, 1.0, v81
	v_add_f32_e32 v81, v82, v130
	v_mul_f32_e32 v84, 0xbfb8aa3b, v84
	v_mul_f32_e32 v85, 0xbfb8aa3b, v85
	v_add_f32_e32 v86, v86, v134
	v_add_f32_e32 v87, v87, v135
	v_mul_f32_e32 v81, 0xbfb8aa3b, v81
	v_add_f32_e32 v82, v83, v131
	v_exp_f32_e32 v84, v84
	v_exp_f32_e32 v85, v85
	v_mul_f32_e32 v86, 0xbfb8aa3b, v86
	v_mul_f32_e32 v87, 0xbfb8aa3b, v87
	v_exp_f32_e32 v81, v81
	v_mul_f32_e32 v82, 0xbfb8aa3b, v82
	v_exp_f32_e32 v86, v86
	v_exp_f32_e32 v87, v87
	v_exp_f32_e32 v82, v82
	v_add_f32_e32 v84, 1.0, v84
	v_add_f32_e32 v85, 1.0, v85
	v_rcp_f32_e32 v83, v80
	v_add_f32_e32 v80, 1.0, v81
	v_rcp_f32_e32 v84, v84
	v_rcp_f32_e32 v85, v85
	v_add_f32_e32 v86, 1.0, v86
	v_add_f32_e32 v87, 1.0, v87
	v_rcp_f32_e32 v89, v80
	v_add_f32_e32 v80, 1.0, v82
	v_rcp_f32_e32 v86, v86
	v_rcp_f32_e32 v87, v87
	v_rcp_f32_e32 v90, v80
	s_mov_b32 s0, 0xa000
	v_cvt_pk_bf16_f32 v80, v84, v85
	v_add_co_u32_e32 v84, vcc, s0, v154
	v_cvt_pk_bf16_f32 v81, v86, v87
	v_cvt_pk_bf16_f32 v82, v88, v83
	v_cvt_pk_bf16_f32 v83, v89, v90
	v_addc_co_u32_e32 v85, vcc, 0, v155, vcc
	global_store_dwordx4 v[84:85], v[80:83], off
	v_add_f32_e32 v72, v72, v128
	v_mul_f32_e32 v72, 0xbfb8aa3b, v72
	v_add_f32_e32 v73, v73, v129
	v_exp_f32_e32 v72, v72
	v_mul_f32_e32 v73, 0xbfb8aa3b, v73
	v_exp_f32_e32 v73, v73
	v_add_f32_e32 v76, v76, v132
	v_add_f32_e32 v72, 1.0, v72
	v_add_f32_e32 v77, v77, v133
	v_rcp_f32_e32 v80, v72
	v_add_f32_e32 v72, 1.0, v73
	v_add_f32_e32 v73, v74, v130
	v_mul_f32_e32 v76, 0xbfb8aa3b, v76
	v_mul_f32_e32 v77, 0xbfb8aa3b, v77
	v_add_f32_e32 v78, v78, v134
	v_add_f32_e32 v79, v79, v135
	v_mul_f32_e32 v73, 0xbfb8aa3b, v73
	v_add_f32_e32 v74, v75, v131
	v_exp_f32_e32 v76, v76
	v_exp_f32_e32 v77, v77
	v_mul_f32_e32 v78, 0xbfb8aa3b, v78
	v_mul_f32_e32 v79, 0xbfb8aa3b, v79
	v_exp_f32_e32 v73, v73
	v_mul_f32_e32 v74, 0xbfb8aa3b, v74
	v_exp_f32_e32 v78, v78
	v_exp_f32_e32 v79, v79
	v_exp_f32_e32 v74, v74
	v_add_f32_e32 v76, 1.0, v76
	v_add_f32_e32 v77, 1.0, v77
	v_rcp_f32_e32 v75, v72
	v_add_f32_e32 v72, 1.0, v73
	v_rcp_f32_e32 v76, v76
	v_rcp_f32_e32 v77, v77
	v_add_f32_e32 v78, 1.0, v78
	v_add_f32_e32 v79, 1.0, v79
	v_rcp_f32_e32 v81, v72
	v_add_f32_e32 v72, 1.0, v74
	v_rcp_f32_e32 v78, v78
	v_rcp_f32_e32 v79, v79
	v_rcp_f32_e32 v82, v72
	s_mov_b32 s0, 0xc000
	v_cvt_pk_bf16_f32 v72, v76, v77
	v_add_co_u32_e32 v76, vcc, s0, v154
	v_cvt_pk_bf16_f32 v73, v78, v79
	v_cvt_pk_bf16_f32 v74, v80, v75
	v_cvt_pk_bf16_f32 v75, v81, v82
	v_addc_co_u32_e32 v77, vcc, 0, v155, vcc
	global_store_dwordx4 v[76:77], v[72:75], off
	v_add_f32_e32 v64, v64, v128
	v_mul_f32_e32 v64, 0xbfb8aa3b, v64
	v_add_f32_e32 v65, v65, v129
	v_exp_f32_e32 v64, v64
	v_mul_f32_e32 v65, 0xbfb8aa3b, v65
	v_exp_f32_e32 v65, v65
	v_add_f32_e32 v68, v68, v132
	v_add_f32_e32 v64, 1.0, v64
	v_add_f32_e32 v69, v69, v133
	v_rcp_f32_e32 v72, v64
	v_add_f32_e32 v64, 1.0, v65
	v_add_f32_e32 v65, v66, v130
	v_mul_f32_e32 v68, 0xbfb8aa3b, v68
	v_mul_f32_e32 v69, 0xbfb8aa3b, v69
	v_add_f32_e32 v70, v70, v134
	v_add_f32_e32 v71, v71, v135
	v_mul_f32_e32 v65, 0xbfb8aa3b, v65
	v_add_f32_e32 v66, v67, v131
	v_exp_f32_e32 v68, v68
	v_exp_f32_e32 v69, v69
; __device__ __forceinline__ float sigmoidf_(float x) { return __builtin_amdgcn_rcpf(1.f + __expf(-x)); }
; __device__ __forceinline__ void phaseE(const Params& p, int layer) {
;     ...
;         for (int ai = 0; ai < 2; ai++)
; #pragma unroll
;           for (int bj = 0; bj < 2; bj++)
; #pragma unroll
;             for (int m = 0; m < 4; m++) {
;               unsigned q[4];
; #pragma unroll
;               for (int n = 0; n < 2; n++) {
;                 const float4 bg = bgv[bj][n];
;                 f32x4 v = acc[ai][bj][m][n];
;                 q[2 * n] = pk2(sigmoidf_(v[0] + bg.x), sigmoidf_(v[1] + bg.y));
;                 q[2 * n + 1] = pk2(sigmoidf_(v[2] + bg.z), sigmoidf_(v[3] + bg.w));
;               }
;               *(uint4*)(gsb + ((ai * 2 + bj) * 4 + m) * 8192 + gs_lane) = make_uint4(q[0], q[1], q[2], q[3]);
;               __builtin_amdgcn_sched_barrier(0);
;             }
	v_mul_f32_e32 v70, 0xbfb8aa3b, v70
	v_mul_f32_e32 v71, 0xbfb8aa3b, v71
	v_exp_f32_e32 v65, v65
	v_mul_f32_e32 v66, 0xbfb8aa3b, v66
	v_exp_f32_e32 v70, v70
	v_exp_f32_e32 v71, v71
	v_exp_f32_e32 v66, v66
	v_add_f32_e32 v68, 1.0, v68
	v_add_f32_e32 v69, 1.0, v69
	v_rcp_f32_e32 v67, v64
	v_add_f32_e32 v64, 1.0, v65
	v_rcp_f32_e32 v68, v68
	v_rcp_f32_e32 v69, v69
	v_add_f32_e32 v70, 1.0, v70
	v_add_f32_e32 v71, 1.0, v71
	v_rcp_f32_e32 v73, v64
	v_add_f32_e32 v64, 1.0, v66
	v_rcp_f32_e32 v70, v70
	v_rcp_f32_e32 v71, v71
	v_rcp_f32_e32 v74, v64
	s_mov_b32 s0, 0xe000
	v_cvt_pk_bf16_f32 v64, v68, v69
	v_add_co_u32_e32 v68, vcc, s0, v154
	v_cvt_pk_bf16_f32 v65, v70, v71
	v_cvt_pk_bf16_f32 v66, v72, v67
	v_cvt_pk_bf16_f32 v67, v73, v74
	v_addc_co_u32_e32 v69, vcc, 0, v155, vcc
	global_store_dwordx4 v[68:69], v[64:67], off
	v_add_f32_e32 v56, v56, v136
	v_mul_f32_e32 v56, 0xbfb8aa3b, v56
	v_add_f32_e32 v57, v57, v137
	v_exp_f32_e32 v56, v56
	v_mul_f32_e32 v57, 0xbfb8aa3b, v57
	v_exp_f32_e32 v57, v57
	v_add_f32_e32 v60, v60, v140
	v_add_f32_e32 v56, 1.0, v56
	v_add_f32_e32 v61, v61, v141
	v_rcp_f32_e32 v64, v56
	v_add_f32_e32 v56, 1.0, v57
	v_add_f32_e32 v57, v58, v138
	v_mul_f32_e32 v60, 0xbfb8aa3b, v60
	v_mul_f32_e32 v61, 0xbfb8aa3b, v61
	v_add_f32_e32 v62, v62, v142
	v_add_f32_e32 v63, v63, v143
	v_mul_f32_e32 v57, 0xbfb8aa3b, v57
	v_add_f32_e32 v58, v59, v139
	v_exp_f32_e32 v60, v60
	v_exp_f32_e32 v61, v61
	v_mul_f32_e32 v62, 0xbfb8aa3b, v62
	v_mul_f32_e32 v63, 0xbfb8aa3b, v63
	v_exp_f32_e32 v57, v57
	v_mul_f32_e32 v58, 0xbfb8aa3b, v58
	v_exp_f32_e32 v62, v62
	v_exp_f32_e32 v63, v63
	v_exp_f32_e32 v58, v58
	v_add_f32_e32 v60, 1.0, v60
	v_add_f32_e32 v61, 1.0, v61
	v_rcp_f32_e32 v59, v56
	v_add_f32_e32 v56, 1.0, v57
	v_rcp_f32_e32 v60, v60
	v_rcp_f32_e32 v61, v61
	v_add_f32_e32 v62, 1.0, v62
	v_add_f32_e32 v63, 1.0, v63
	v_rcp_f32_e32 v65, v56
	v_add_f32_e32 v56, 1.0, v58
	v_rcp_f32_e32 v62, v62
	v_rcp_f32_e32 v63, v63
	v_rcp_f32_e32 v66, v56
	v_cvt_pk_bf16_f32 v56, v60, v61
	v_add_co_u32_e32 v60, vcc, s95, v154
	v_cvt_pk_bf16_f32 v57, v62, v63
	v_cvt_pk_bf16_f32 v58, v64, v59
	v_cvt_pk_bf16_f32 v59, v65, v66
	v_addc_co_u32_e32 v61, vcc, 0, v155, vcc
	global_store_dwordx4 v[60:61], v[56:59], off
	v_add_f32_e32 v48, v48, v136
	v_mul_f32_e32 v48, 0xbfb8aa3b, v48
	v_add_f32_e32 v49, v49, v137
	v_exp_f32_e32 v48, v48
	v_mul_f32_e32 v49, 0xbfb8aa3b, v49
	v_exp_f32_e32 v49, v49
	v_add_f32_e32 v52, v52, v140
	v_add_f32_e32 v48, 1.0, v48
	v_add_f32_e32 v53, v53, v141
	v_rcp_f32_e32 v56, v48
	v_add_f32_e32 v48, 1.0, v49
	v_add_f32_e32 v49, v50, v138
	v_mul_f32_e32 v52, 0xbfb8aa3b, v52
	v_mul_f32_e32 v53, 0xbfb8aa3b, v53
	v_add_f32_e32 v54, v54, v142
	v_add_f32_e32 v55, v55, v143
	v_mul_f32_e32 v49, 0xbfb8aa3b, v49
	v_add_f32_e32 v50, v51, v139
	v_exp_f32_e32 v52, v52
	v_exp_f32_e32 v53, v53
	v_mul_f32_e32 v54, 0xbfb8aa3b, v54
	v_mul_f32_e32 v55, 0xbfb8aa3b, v55
	v_exp_f32_e32 v49, v49
	v_mul_f32_e32 v50, 0xbfb8aa3b, v50
	v_exp_f32_e32 v54, v54
	v_exp_f32_e32 v55, v55
	v_exp_f32_e32 v50, v50
	v_add_f32_e32 v52, 1.0, v52
	v_add_f32_e32 v53, 1.0, v53
	v_rcp_f32_e32 v51, v48
	v_add_f32_e32 v48, 1.0, v49
	v_rcp_f32_e32 v52, v52
	v_rcp_f32_e32 v53, v53
	v_add_f32_e32 v54, 1.0, v54
	v_add_f32_e32 v55, 1.0, v55
	v_rcp_f32_e32 v57, v48
	v_add_f32_e32 v48, 1.0, v50
	v_rcp_f32_e32 v54, v54
	v_rcp_f32_e32 v55, v55
	v_rcp_f32_e32 v58, v48
	s_mov_b32 s0, 0x12000
	v_cvt_pk_bf16_f32 v48, v52, v53
	v_add_co_u32_e32 v52, vcc, s0, v154
	v_cvt_pk_bf16_f32 v49, v54, v55
	v_cvt_pk_bf16_f32 v50, v56, v51
	v_cvt_pk_bf16_f32 v51, v57, v58
	v_addc_co_u32_e32 v53, vcc, 0, v155, vcc
	global_store_dwordx4 v[52:53], v[48:51], off
	v_add_f32_e32 v40, v40, v136
	v_mul_f32_e32 v40, 0xbfb8aa3b, v40
	v_add_f32_e32 v41, v41, v137
	v_exp_f32_e32 v40, v40
	v_mul_f32_e32 v41, 0xbfb8aa3b, v41
	v_exp_f32_e32 v41, v41
	v_add_f32_e32 v44, v44, v140
	v_add_f32_e32 v40, 1.0, v40
	v_add_f32_e32 v45, v45, v141
	v_rcp_f32_e32 v48, v40
	v_add_f32_e32 v40, 1.0, v41
	v_add_f32_e32 v41, v42, v138
	v_mul_f32_e32 v44, 0xbfb8aa3b, v44
	v_mul_f32_e32 v45, 0xbfb8aa3b, v45
	v_add_f32_e32 v46, v46, v142
	v_add_f32_e32 v47, v47, v143
	v_mul_f32_e32 v41, 0xbfb8aa3b, v41
	v_add_f32_e32 v42, v43, v139
	v_exp_f32_e32 v44, v44
	v_exp_f32_e32 v45, v45
	v_mul_f32_e32 v46, 0xbfb8aa3b, v46
	v_mul_f32_e32 v47, 0xbfb8aa3b, v47
	v_exp_f32_e32 v41, v41
	v_mul_f32_e32 v42, 0xbfb8aa3b, v42
	v_exp_f32_e32 v46, v46
	v_exp_f32_e32 v47, v47
	v_exp_f32_e32 v42, v42
	v_add_f32_e32 v44, 1.0, v44
	v_add_f32_e32 v45, 1.0, v45
	v_rcp_f32_e32 v43, v40
	v_add_f32_e32 v40, 1.0, v41
	v_rcp_f32_e32 v44, v44
	v_rcp_f32_e32 v45, v45
	v_add_f32_e32 v46, 1.0, v46
	v_add_f32_e32 v47, 1.0, v47
	v_rcp_f32_e32 v49, v40
	v_add_f32_e32 v40, 1.0, v42
	v_rcp_f32_e32 v46, v46
	v_rcp_f32_e32 v47, v47
	v_rcp_f32_e32 v50, v40
	s_mov_b32 s0, 0x14000
	v_cvt_pk_bf16_f32 v40, v44, v45
	v_add_co_u32_e32 v44, vcc, s0, v154
	v_cvt_pk_bf16_f32 v41, v46, v47
	v_cvt_pk_bf16_f32 v42, v48, v43
	v_cvt_pk_bf16_f32 v43, v49, v50
	v_addc_co_u32_e32 v45, vcc, 0, v155, vcc
	global_store_dwordx4 v[44:45], v[40:43], off
	v_add_f32_e32 v32, v32, v136
	v_mul_f32_e32 v32, 0xbfb8aa3b, v32
	v_add_f32_e32 v33, v33, v137
	v_exp_f32_e32 v32, v32
	v_mul_f32_e32 v33, 0xbfb8aa3b, v33
	v_exp_f32_e32 v33, v33
	v_add_f32_e32 v36, v36, v140
	v_add_f32_e32 v32, 1.0, v32
	v_add_f32_e32 v37, v37, v141
	v_rcp_f32_e32 v40, v32
	v_add_f32_e32 v32, 1.0, v33
	v_add_f32_e32 v33, v34, v138
	v_mul_f32_e32 v36, 0xbfb8aa3b, v36
	v_mul_f32_e32 v37, 0xbfb8aa3b, v37
	v_add_f32_e32 v38, v38, v142
	v_add_f32_e32 v39, v39, v143
	v_mul_f32_e32 v33, 0xbfb8aa3b, v33
	v_add_f32_e32 v34, v35, v139
	v_exp_f32_e32 v36, v36
; __device__ __forceinline__ float sigmoidf_(float x) { return __builtin_amdgcn_rcpf(1.f + __expf(-x)); }
; __device__ __forceinline__ void phaseE(const Params& p, int layer) {
;     ...
;         for (int ai = 0; ai < 2; ai++)
; #pragma unroll
;           for (int bj = 0; bj < 2; bj++)
; #pragma unroll
;             for (int m = 0; m < 4; m++) {
;               unsigned q[4];
; #pragma unroll
;               for (int n = 0; n < 2; n++) {
;                 const float4 bg = bgv[bj][n];
;                 f32x4 v = acc[ai][bj][m][n];
;                 q[2 * n] = pk2(sigmoidf_(v[0] + bg.x), sigmoidf_(v[1] + bg.y));
;                 q[2 * n + 1] = pk2(sigmoidf_(v[2] + bg.z), sigmoidf_(v[3] + bg.w));
;               }
;               *(uint4*)(gsb + ((ai * 2 + bj) * 4 + m) * 8192 + gs_lane) = make_uint4(q[0], q[1], q[2], q[3]);
;               __builtin_amdgcn_sched_barrier(0);
;             }
	v_exp_f32_e32 v37, v37
	v_mul_f32_e32 v38, 0xbfb8aa3b, v38
	v_mul_f32_e32 v39, 0xbfb8aa3b, v39
	v_exp_f32_e32 v33, v33
	v_mul_f32_e32 v34, 0xbfb8aa3b, v34
	v_exp_f32_e32 v38, v38
	v_exp_f32_e32 v39, v39
	v_exp_f32_e32 v34, v34
	v_add_f32_e32 v36, 1.0, v36
	v_add_f32_e32 v37, 1.0, v37
	v_rcp_f32_e32 v35, v32
	v_add_f32_e32 v32, 1.0, v33
	v_rcp_f32_e32 v36, v36
	v_rcp_f32_e32 v37, v37
	v_add_f32_e32 v38, 1.0, v38
	v_add_f32_e32 v39, 1.0, v39
	v_rcp_f32_e32 v41, v32
	v_add_f32_e32 v32, 1.0, v34
	v_rcp_f32_e32 v38, v38
	v_rcp_f32_e32 v39, v39
	v_rcp_f32_e32 v42, v32
	s_mov_b32 s0, 0x16000
	v_cvt_pk_bf16_f32 v32, v36, v37
	v_add_co_u32_e32 v36, vcc, s0, v154
	v_cvt_pk_bf16_f32 v33, v38, v39
	v_cvt_pk_bf16_f32 v34, v40, v35
	v_cvt_pk_bf16_f32 v35, v41, v42
	v_addc_co_u32_e32 v37, vcc, 0, v155, vcc
	global_store_dwordx4 v[36:37], v[32:35], off
	v_add_f32_e32 v24, v24, v128
	v_mul_f32_e32 v24, 0xbfb8aa3b, v24
	v_add_f32_e32 v25, v25, v129
	v_exp_f32_e32 v24, v24
	v_mul_f32_e32 v25, 0xbfb8aa3b, v25
	v_exp_f32_e32 v25, v25
	v_add_f32_e32 v28, v28, v132
	v_add_f32_e32 v24, 1.0, v24
	v_add_f32_e32 v29, v29, v133
	v_rcp_f32_e32 v32, v24
	v_add_f32_e32 v24, 1.0, v25
	v_add_f32_e32 v25, v26, v130
	v_mul_f32_e32 v28, 0xbfb8aa3b, v28
	v_mul_f32_e32 v29, 0xbfb8aa3b, v29
	v_add_f32_e32 v30, v30, v134
	v_add_f32_e32 v31, v31, v135
	v_mul_f32_e32 v25, 0xbfb8aa3b, v25
	v_add_f32_e32 v26, v27, v131
	v_exp_f32_e32 v28, v28
	v_exp_f32_e32 v29, v29
	v_mul_f32_e32 v30, 0xbfb8aa3b, v30
	v_mul_f32_e32 v31, 0xbfb8aa3b, v31
	v_exp_f32_e32 v25, v25
	v_mul_f32_e32 v26, 0xbfb8aa3b, v26
	v_exp_f32_e32 v30, v30
	v_exp_f32_e32 v31, v31
	v_exp_f32_e32 v26, v26
	v_add_f32_e32 v28, 1.0, v28
	v_add_f32_e32 v29, 1.0, v29
	v_rcp_f32_e32 v27, v24
	v_add_f32_e32 v24, 1.0, v25
	v_rcp_f32_e32 v28, v28
	v_rcp_f32_e32 v29, v29
	v_add_f32_e32 v30, 1.0, v30
	v_add_f32_e32 v31, 1.0, v31
	v_rcp_f32_e32 v33, v24
	v_add_f32_e32 v24, 1.0, v26
	v_rcp_f32_e32 v30, v30
	v_rcp_f32_e32 v31, v31
	v_rcp_f32_e32 v34, v24
	s_mov_b32 s0, 0x18000
	v_cvt_pk_bf16_f32 v24, v28, v29
	v_add_co_u32_e32 v28, vcc, s0, v154
	v_cvt_pk_bf16_f32 v25, v30, v31
	v_cvt_pk_bf16_f32 v26, v32, v27
	v_cvt_pk_bf16_f32 v27, v33, v34
	v_addc_co_u32_e32 v29, vcc, 0, v155, vcc
	global_store_dwordx4 v[28:29], v[24:27], off
	v_add_f32_e32 v16, v16, v128
	v_mul_f32_e32 v16, 0xbfb8aa3b, v16
	v_add_f32_e32 v17, v17, v129
	v_exp_f32_e32 v16, v16
	v_mul_f32_e32 v17, 0xbfb8aa3b, v17
	v_exp_f32_e32 v17, v17
	v_add_f32_e32 v20, v20, v132
	v_add_f32_e32 v16, 1.0, v16
	v_add_f32_e32 v21, v21, v133
	v_rcp_f32_e32 v24, v16
	v_add_f32_e32 v16, 1.0, v17
	v_add_f32_e32 v17, v18, v130
	v_mul_f32_e32 v20, 0xbfb8aa3b, v20
	v_mul_f32_e32 v21, 0xbfb8aa3b, v21
	v_add_f32_e32 v22, v22, v134
	v_add_f32_e32 v23, v23, v135
	v_mul_f32_e32 v17, 0xbfb8aa3b, v17
	v_add_f32_e32 v18, v19, v131
	v_exp_f32_e32 v20, v20
	v_exp_f32_e32 v21, v21
	v_mul_f32_e32 v22, 0xbfb8aa3b, v22
	v_mul_f32_e32 v23, 0xbfb8aa3b, v23
	v_exp_f32_e32 v17, v17
	v_mul_f32_e32 v18, 0xbfb8aa3b, v18
	v_exp_f32_e32 v22, v22
	v_exp_f32_e32 v23, v23
	v_exp_f32_e32 v18, v18
	v_add_f32_e32 v20, 1.0, v20
	v_add_f32_e32 v21, 1.0, v21
	v_rcp_f32_e32 v19, v16
	v_add_f32_e32 v16, 1.0, v17
	v_rcp_f32_e32 v20, v20
	v_rcp_f32_e32 v21, v21
	v_add_f32_e32 v22, 1.0, v22
	v_add_f32_e32 v23, 1.0, v23
	v_rcp_f32_e32 v25, v16
	v_add_f32_e32 v16, 1.0, v18
	v_rcp_f32_e32 v22, v22
	v_rcp_f32_e32 v23, v23
	v_rcp_f32_e32 v26, v16
	s_mov_b32 s0, 0x1a000
	v_cvt_pk_bf16_f32 v16, v20, v21
	v_add_co_u32_e32 v20, vcc, s0, v154
	v_cvt_pk_bf16_f32 v17, v22, v23
	v_cvt_pk_bf16_f32 v18, v24, v19
	v_cvt_pk_bf16_f32 v19, v25, v26
	v_addc_co_u32_e32 v21, vcc, 0, v155, vcc
	global_store_dwordx4 v[20:21], v[16:19], off
	v_add_f32_e32 v8, v8, v128
	v_mul_f32_e32 v8, 0xbfb8aa3b, v8
	v_add_f32_e32 v9, v9, v129
	v_exp_f32_e32 v8, v8
	v_mul_f32_e32 v9, 0xbfb8aa3b, v9
	v_exp_f32_e32 v9, v9
	v_add_f32_e32 v12, v12, v132
	v_add_f32_e32 v8, 1.0, v8
	v_add_f32_e32 v13, v13, v133
	v_rcp_f32_e32 v16, v8
	v_add_f32_e32 v8, 1.0, v9
	v_add_f32_e32 v9, v10, v130
	v_mul_f32_e32 v12, 0xbfb8aa3b, v12
	v_mul_f32_e32 v13, 0xbfb8aa3b, v13
	v_add_f32_e32 v14, v14, v134
	v_add_f32_e32 v15, v15, v135
	v_mul_f32_e32 v9, 0xbfb8aa3b, v9
	v_add_f32_e32 v10, v11, v131
	v_exp_f32_e32 v12, v12
	v_exp_f32_e32 v13, v13
	v_mul_f32_e32 v14, 0xbfb8aa3b, v14
	v_mul_f32_e32 v15, 0xbfb8aa3b, v15
	v_exp_f32_e32 v9, v9
	v_mul_f32_e32 v10, 0xbfb8aa3b, v10
	v_exp_f32_e32 v14, v14
	v_exp_f32_e32 v15, v15
	v_exp_f32_e32 v10, v10
	v_add_f32_e32 v12, 1.0, v12
	v_add_f32_e32 v13, 1.0, v13
	v_rcp_f32_e32 v11, v8
	v_add_f32_e32 v8, 1.0, v9
	v_rcp_f32_e32 v12, v12
	v_rcp_f32_e32 v13, v13
	v_add_f32_e32 v14, 1.0, v14
	v_add_f32_e32 v15, 1.0, v15
	v_rcp_f32_e32 v17, v8
	v_add_f32_e32 v8, 1.0, v10
	v_rcp_f32_e32 v14, v14
	v_rcp_f32_e32 v15, v15
	v_rcp_f32_e32 v18, v8
	s_mov_b32 s0, 0x1c000
	v_cvt_pk_bf16_f32 v8, v12, v13
	v_add_co_u32_e32 v12, vcc, s0, v154
	v_cvt_pk_bf16_f32 v9, v14, v15
	v_cvt_pk_bf16_f32 v10, v16, v11
	v_cvt_pk_bf16_f32 v11, v17, v18
	v_addc_co_u32_e32 v13, vcc, 0, v155, vcc
	global_store_dwordx4 v[12:13], v[8:11], off
	v_add_f32_e32 v0, v0, v128
	v_mul_f32_e32 v0, 0xbfb8aa3b, v0
	v_add_f32_e32 v1, v1, v129
	v_exp_f32_e32 v0, v0
	v_mul_f32_e32 v1, 0xbfb8aa3b, v1
	v_exp_f32_e32 v1, v1
	v_add_f32_e32 v4, v4, v132
	v_add_f32_e32 v0, 1.0, v0
	v_add_f32_e32 v5, v5, v133
	v_rcp_f32_e32 v8, v0
	v_add_f32_e32 v0, 1.0, v1
	v_add_f32_e32 v1, v2, v130
	v_mul_f32_e32 v4, 0xbfb8aa3b, v4
	v_mul_f32_e32 v5, 0xbfb8aa3b, v5
	v_add_f32_e32 v6, v6, v134
	v_add_f32_e32 v7, v7, v135
	v_mul_f32_e32 v1, 0xbfb8aa3b, v1
	v_add_f32_e32 v2, v3, v131
	v_exp_f32_e32 v4, v4
	v_exp_f32_e32 v5, v5
	v_mul_f32_e32 v6, 0xbfb8aa3b, v6
	v_mul_f32_e32 v7, 0xbfb8aa3b, v7
	v_exp_f32_e32 v1, v1
	v_mul_f32_e32 v2, 0xbfb8aa3b, v2
	v_exp_f32_e32 v6, v6
	v_exp_f32_e32 v7, v7
	v_exp_f32_e32 v2, v2
	v_add_f32_e32 v4, 1.0, v4
	v_add_f32_e32 v5, 1.0, v5
	v_rcp_f32_e32 v3, v0
	v_add_f32_e32 v0, 1.0, v1
	v_rcp_f32_e32 v4, v4
	v_rcp_f32_e32 v5, v5
	v_add_f32_e32 v6, 1.0, v6
	v_add_f32_e32 v7, 1.0, v7
	v_rcp_f32_e32 v9, v0
	v_add_f32_e32 v0, 1.0, v2
	v_rcp_f32_e32 v6, v6
	v_rcp_f32_e32 v7, v7
	v_rcp_f32_e32 v10, v0
	v_cvt_pk_bf16_f32 v0, v4, v5
	v_add_co_u32_e32 v4, vcc, 0x1e000, v154
	v_cvt_pk_bf16_f32 v1, v6, v7
	v_cvt_pk_bf16_f32 v2, v8, v3
	v_cvt_pk_bf16_f32 v3, v9, v10
	v_addc_co_u32_e32 v5, vcc, 0, v155, vcc
	global_store_dwordx4 v[4:5], v[0:3], off
	v_mov_b64_e32 v[142:143], v[146:147]
	v_mov_b64_e32 v[140:141], v[148:149]
	v_mov_b64_e32 v[138:139], v[150:151]
	v_mov_b64_e32 v[136:137], v[152:153]
	s_branch .LBB0_2313
